# EpiMerge: gate loads batched for all three variants (tail part, branch A kept, branch B stored)
# speedup vs baseline: 1.0520x; 1.0065x over previous
;     __device__ __forceinline__ void operator()(AccT& acc, const pg8::Unit& u, int wr, int wc, int fr_, int fq_) const {
;         int fr = fr_, fq = fq_; asm volatile("" : "+v"(fr), "+v"(fq));
;         const int row0 = u.pm * 256 + wr * 64 + fr, col0 = u.pn * 256 + wc * 32 + 8 * fq;
;         const bf16_t* GA = (const bf16_t*)(ws + WS_GA); const bf16_t* GB = (const bf16_t*)(ws + WS_GB);
;         bf16_t* MB = (bf16_t*)(ws + WS_SG);
;         if (u.sub & 2) {
;             const bf16_t* G = (u.sub & 1) ? GB : GA;
;             bf16_t* P = (bf16_t*)(ws + WS_PART2) + (size_t)u.sp * (2048 * D);
; #pragma unroll
;             for (int ai = 0; ai < 2; ++ai)
; #pragma unroll
;                 for (int m = 0; m < 4; ++m) {
;                     const size_t ro = (size_t)(row0 + ai * 128 + m * 16) * D + col0;
;                     const size_t po = (size_t)(row0 - 16384 + ai * 128 + m * 16) * D + col0;
; #pragma unroll
;                     for (int bj = 0; bj < 2; ++bj) {
;                         const u32x4 gv = *(const u32x4*)(G + ro + bj * 128);
;                         f32x4 s0, s1; s0[0] = bflo(gv[0]); s0[1] = bfhi(gv[0]); s0[2] = bflo(gv[1]); s0[3] = bfhi(gv[1]); s1[0] = bflo(gv[2]); s1[1] = bfhi(gv[2]); s1[2] = bflo(gv[3]); s1[3] = bfhi(gv[3]);
;                         const f32x4 t0 = s0 * acc[ai][bj][m][0], t1 = s1 * acc[ai][bj][m][1];
;                         u32x4 o; o[0] = pk2(t0[0], t0[1]); o[1] = pk2(t0[2], t0[3]); o[2] = pk2(t1[0], t1[1]); o[3] = pk2(t1[2], t1[3]);
;                         *(u32x4*)(P + po + bj * 128) = o;
;                     }
;                 }
;             return;
;         }
; #pragma unroll
;         for (int ai = 0; ai < 2; ++ai)
; #pragma unroll
;             for (int m = 0; m < 4; ++m) {
;                 const size_t ro = (size_t)(row0 + ai * 128 + m * 16) * D + col0;
; #pragma unroll
;                 for (int bj = 0; bj < 2; ++bj) {
;                     const size_t o = ro + bj * 128;
;                     const u32x4 gb = *(const u32x4*)(GB + o);
;                     f32x4 b0, b1;
;                     b0[0] = fmaxf(bflo(gb[0]), 1e-6f); b0[1] = fmaxf(bfhi(gb[0]), 1e-6f); b0[2] = fmaxf(bflo(gb[1]), 1e-6f); b0[3] = fmaxf(bfhi(gb[1]), 1e-6f);
;                     b1[0] = fmaxf(bflo(gb[2]), 1e-6f); b1[1] = fmaxf(bfhi(gb[2]), 1e-6f); b1[2] = fmaxf(bflo(gb[3]), 1e-6f); b1[3] = fmaxf(bfhi(gb[3]), 1e-6f);
.LBB0_476:
	s_lshl_b32 s2, s6, 8
	v_mov_b32_e32 v0, v141
	v_mov_b32_e32 v3, v143
	s_add_i32 s2, s2, s77
	s_mov_b64 s[4:5], -1
	v_add_u32_e32 v2, s2, v0
	s_lshl_b32 s2, s12, 8
	s_or_b32 s2, s2, s78
	v_lshl_add_u32 v146, v3, 3, s2
	s_bitcmp1_b32 s39, 1
	v_ashrrev_i32_e32 v147, 31, v146
	v_ashrrev_i32_e32 v3, 31, v2
	v_lshlrev_b32_e32 v148, 11, v2
	v_lshl_add_u32 v148, v146, 1, v148
	s_cbranch_scc1 .Lmg_tail
	s_bitcmp1_b32 s39, 0
	s_cbranch_scc1 .Lmg_sub1
	s_mov_b32 s98, s56
	s_mov_b32 s99, s57
	s_mov_b32 s100, s54
	s_mov_b32 s101, s55
	global_load_dwordx4 v[190:193], v148, s[98:99]
	global_load_dwordx4 v[194:197], v148, s[100:101]
	global_load_dwordx4 v[198:201], v148, s[98:99] offset:256
	global_load_dwordx4 v[202:205], v148, s[100:101] offset:256
	s_add_u32 s98, s56, 0x8000
	s_addc_u32 s99, s57, 0
	s_add_u32 s100, s54, 0x8000
	s_addc_u32 s101, s55, 0
	global_load_dwordx4 v[206:209], v148, s[98:99]
	global_load_dwordx4 v[210:213], v148, s[100:101]
	global_load_dwordx4 v[214:217], v148, s[98:99] offset:256
	global_load_dwordx4 v[218:221], v148, s[100:101] offset:256
	s_add_u32 s98, s56, 0x10000
	s_addc_u32 s99, s57, 0
	s_add_u32 s100, s54, 0x10000
	s_addc_u32 s101, s55, 0
	global_load_dwordx4 v[222:225], v148, s[98:99]
	global_load_dwordx4 v[226:229], v148, s[100:101]
	global_load_dwordx4 v[230:233], v148, s[98:99] offset:256
	global_load_dwordx4 v[234:237], v148, s[100:101] offset:256
	s_add_u32 s98, s56, 0x18000
	s_addc_u32 s99, s57, 0
	s_add_u32 s100, s54, 0x18000
	s_addc_u32 s101, s55, 0
	global_load_dwordx4 v[238:241], v148, s[98:99]
	global_load_dwordx4 v[242:245], v148, s[100:101]
	global_load_dwordx4 v[246:249], v148, s[98:99] offset:256
	global_load_dwordx4 v[250:253], v148, s[100:101] offset:256
	s_waitcnt vmcnt(14)
	v_lshlrev_b32_e32 v154, 16, v190
	v_and_b32_e32 v155, 0xffff0000, v190
	v_lshlrev_b32_e32 v156, 16, v191
	v_and_b32_e32 v157, 0xffff0000, v191
	v_lshlrev_b32_e32 v158, 16, v192
	v_and_b32_e32 v159, 0xffff0000, v192
	v_lshlrev_b32_e32 v162, 16, v193
	v_and_b32_e32 v163, 0xffff0000, v193
	v_max_f32_e32 v154, v154, v154
	v_max_f32_e32 v155, v155, v155
	v_max_f32_e32 v156, v156, v156
	v_max_f32_e32 v157, v157, v157
	v_max_f32_e32 v158, v158, v158
	v_max_f32_e32 v159, v159, v159
	v_max_f32_e32 v162, v162, v162
	v_max_f32_e32 v163, v163, v163
	v_max_f32_e32 v154, 0x358637bd, v154
	v_max_f32_e32 v155, 0x358637bd, v155
	v_max_f32_e32 v156, 0x358637bd, v156
	v_max_f32_e32 v157, 0x358637bd, v157
	v_max_f32_e32 v158, 0x358637bd, v158
	v_max_f32_e32 v159, 0x358637bd, v159
	v_max_f32_e32 v162, 0x358637bd, v162
	v_max_f32_e32 v163, 0x358637bd, v163
	v_rcp_f32_e32 v154, v154
	v_rcp_f32_e32 v155, v155
	v_rcp_f32_e32 v156, v156
	v_rcp_f32_e32 v157, v157
	v_rcp_f32_e32 v158, v158
	v_rcp_f32_e32 v159, v159
	v_rcp_f32_e32 v162, v162
	v_rcp_f32_e32 v163, v163
	v_lshlrev_b32_e32 v150, 16, v194
	v_and_b32_e32 v151, 0xffff0000, v194
	v_pk_mul_f32 v[150:151], v[154:155], v[150:151]
	s_nop 0
	v_pk_mul_f32 v[128:129], v[128:129], v[150:151]
	v_lshlrev_b32_e32 v150, 16, v196
	v_and_b32_e32 v151, 0xffff0000, v196
	v_pk_mul_f32 v[150:151], v[158:159], v[150:151]
	s_nop 0
	v_pk_mul_f32 v[124:125], v[124:125], v[150:151]
	v_lshlrev_b32_e32 v150, 16, v195
	v_and_b32_e32 v151, 0xffff0000, v195
	v_pk_mul_f32 v[150:151], v[156:157], v[150:151]
	s_nop 0
	v_pk_mul_f32 v[130:131], v[130:131], v[150:151]
	v_lshlrev_b32_e32 v150, 16, v197
	v_and_b32_e32 v151, 0xffff0000, v197
	v_pk_mul_f32 v[150:151], v[162:163], v[150:151]
	s_nop 0
	v_pk_mul_f32 v[126:127], v[126:127], v[150:151]
	s_waitcnt vmcnt(12)
	v_lshlrev_b32_e32 v154, 16, v198
	v_and_b32_e32 v155, 0xffff0000, v198
	v_lshlrev_b32_e32 v156, 16, v199
	v_and_b32_e32 v157, 0xffff0000, v199
	v_lshlrev_b32_e32 v158, 16, v200
	v_and_b32_e32 v159, 0xffff0000, v200
	v_lshlrev_b32_e32 v162, 16, v201
	v_and_b32_e32 v163, 0xffff0000, v201
	v_max_f32_e32 v154, v154, v154
	v_max_f32_e32 v155, v155, v155
	v_max_f32_e32 v156, v156, v156
	v_max_f32_e32 v157, v157, v157
	v_max_f32_e32 v158, v158, v158
	v_max_f32_e32 v159, v159, v159
	v_max_f32_e32 v162, v162, v162
	v_max_f32_e32 v163, v163, v163
	v_max_f32_e32 v154, 0x358637bd, v154
	v_max_f32_e32 v155, 0x358637bd, v155
	v_max_f32_e32 v156, 0x358637bd, v156
	v_max_f32_e32 v157, 0x358637bd, v157
	v_max_f32_e32 v158, 0x358637bd, v158
	v_max_f32_e32 v159, 0x358637bd, v159
	v_max_f32_e32 v162, 0x358637bd, v162
	v_max_f32_e32 v163, 0x358637bd, v163
	v_rcp_f32_e32 v154, v154
	v_rcp_f32_e32 v155, v155
	v_rcp_f32_e32 v156, v156
	v_rcp_f32_e32 v157, v157
	v_rcp_f32_e32 v158, v158
	v_rcp_f32_e32 v159, v159
	v_rcp_f32_e32 v162, v162
	v_rcp_f32_e32 v163, v163
	v_lshlrev_b32_e32 v150, 16, v202
	v_and_b32_e32 v151, 0xffff0000, v202
	v_pk_mul_f32 v[150:151], v[154:155], v[150:151]
	s_nop 0
	v_pk_mul_f32 v[96:97], v[96:97], v[150:151]
	v_lshlrev_b32_e32 v150, 16, v204
	v_and_b32_e32 v151, 0xffff0000, v204
	v_pk_mul_f32 v[150:151], v[158:159], v[150:151]
	s_nop 0
	v_pk_mul_f32 v[92:93], v[92:93], v[150:151]
	v_lshlrev_b32_e32 v150, 16, v203
	v_and_b32_e32 v151, 0xffff0000, v203
	v_pk_mul_f32 v[150:151], v[156:157], v[150:151]
	s_nop 0
	v_pk_mul_f32 v[98:99], v[98:99], v[150:151]
	v_lshlrev_b32_e32 v150, 16, v205
	v_and_b32_e32 v151, 0xffff0000, v205
	v_pk_mul_f32 v[150:151], v[162:163], v[150:151]
	s_nop 0
	v_pk_mul_f32 v[94:95], v[94:95], v[150:151]
	s_waitcnt vmcnt(10)
; __device__ __forceinline__ float bflo(unsigned u) { return __uint_as_float(u << 16); }
; __device__ __forceinline__ float bfhi(unsigned u) { return __uint_as_float(u & 0xffff0000u); }
; __device__ __forceinline__ float frcp(float x) { return __builtin_amdgcn_rcpf(x); }
;     __device__ __forceinline__ void operator()(AccT& acc, const pg8::Unit& u, int wr, int wc, int fr_, int fq_) const {
;     ...
; #pragma unroll
;         for (int ai = 0; ai < 2; ++ai)
; #pragma unroll
;             for (int m = 0; m < 4; ++m) {
;                 const size_t ro = (size_t)(row0 + ai * 128 + m * 16) * D + col0;
; #pragma unroll
;                 for (int bj = 0; bj < 2; ++bj) {
;                     const size_t o = ro + bj * 128;
;                     const u32x4 gb = *(const u32x4*)(GB + o);
;                     f32x4 b0, b1;
;                     b0[0] = fmaxf(bflo(gb[0]), 1e-6f); b0[1] = fmaxf(bfhi(gb[0]), 1e-6f); b0[2] = fmaxf(bflo(gb[1]), 1e-6f); b0[3] = fmaxf(bfhi(gb[1]), 1e-6f);
;                     b1[0] = fmaxf(bflo(gb[2]), 1e-6f); b1[1] = fmaxf(bfhi(gb[2]), 1e-6f); b1[2] = fmaxf(bflo(gb[3]), 1e-6f); b1[3] = fmaxf(bfhi(gb[3]), 1e-6f);
;                     if ((u.sub & 1) == 0) {
;                         const u32x4 ga = *(const u32x4*)(GA + o);
;                         f32x4 a0, a1; a0[0] = bflo(ga[0]); a0[1] = bfhi(ga[0]); a0[2] = bflo(ga[1]); a0[3] = bfhi(ga[1]); a1[0] = bflo(ga[2]); a1[1] = bfhi(ga[2]); a1[2] = bflo(ga[3]); a1[3] = bfhi(ga[3]);
; #pragma unroll
;                         for (int j = 0; j < 4; ++j) { acc[ai][bj][m][0][j] *= a0[j] * frcp(b0[j]); acc[ai][bj][m][1][j] *= a1[j] * frcp(b1[j]); }
	v_lshlrev_b32_e32 v154, 16, v206
	v_and_b32_e32 v155, 0xffff0000, v206
	v_lshlrev_b32_e32 v156, 16, v207
	v_and_b32_e32 v157, 0xffff0000, v207
	v_lshlrev_b32_e32 v158, 16, v208
	v_and_b32_e32 v159, 0xffff0000, v208
	v_lshlrev_b32_e32 v162, 16, v209
	v_and_b32_e32 v163, 0xffff0000, v209
	v_max_f32_e32 v154, v154, v154
	v_max_f32_e32 v155, v155, v155
	v_max_f32_e32 v156, v156, v156
	v_max_f32_e32 v157, v157, v157
	v_max_f32_e32 v158, v158, v158
	v_max_f32_e32 v159, v159, v159
	v_max_f32_e32 v162, v162, v162
	v_max_f32_e32 v163, v163, v163
	v_max_f32_e32 v154, 0x358637bd, v154
	v_max_f32_e32 v155, 0x358637bd, v155
	v_max_f32_e32 v156, 0x358637bd, v156
	v_max_f32_e32 v157, 0x358637bd, v157
	v_max_f32_e32 v158, 0x358637bd, v158
	v_max_f32_e32 v159, 0x358637bd, v159
	v_max_f32_e32 v162, 0x358637bd, v162
	v_max_f32_e32 v163, 0x358637bd, v163
	v_rcp_f32_e32 v154, v154
	v_rcp_f32_e32 v155, v155
	v_rcp_f32_e32 v156, v156
	v_rcp_f32_e32 v157, v157
	v_rcp_f32_e32 v158, v158
	v_rcp_f32_e32 v159, v159
	v_rcp_f32_e32 v162, v162
	v_rcp_f32_e32 v163, v163
	v_lshlrev_b32_e32 v150, 16, v210
	v_and_b32_e32 v151, 0xffff0000, v210
	v_pk_mul_f32 v[150:151], v[154:155], v[150:151]
	s_nop 0
	v_pk_mul_f32 v[120:121], v[120:121], v[150:151]
	v_lshlrev_b32_e32 v150, 16, v212
	v_and_b32_e32 v151, 0xffff0000, v212
	v_pk_mul_f32 v[150:151], v[158:159], v[150:151]
	s_nop 0
	v_pk_mul_f32 v[116:117], v[116:117], v[150:151]
	v_lshlrev_b32_e32 v150, 16, v211
	v_and_b32_e32 v151, 0xffff0000, v211
	v_pk_mul_f32 v[150:151], v[156:157], v[150:151]
	s_nop 0
	v_pk_mul_f32 v[122:123], v[122:123], v[150:151]
	v_lshlrev_b32_e32 v150, 16, v213
	v_and_b32_e32 v151, 0xffff0000, v213
	v_pk_mul_f32 v[150:151], v[162:163], v[150:151]
	s_nop 0
	v_pk_mul_f32 v[118:119], v[118:119], v[150:151]
	s_waitcnt vmcnt(8)
	v_lshlrev_b32_e32 v154, 16, v214
	v_and_b32_e32 v155, 0xffff0000, v214
	v_lshlrev_b32_e32 v156, 16, v215
	v_and_b32_e32 v157, 0xffff0000, v215
	v_lshlrev_b32_e32 v158, 16, v216
	v_and_b32_e32 v159, 0xffff0000, v216
	v_lshlrev_b32_e32 v162, 16, v217
	v_and_b32_e32 v163, 0xffff0000, v217
	v_max_f32_e32 v154, v154, v154
	v_max_f32_e32 v155, v155, v155
	v_max_f32_e32 v156, v156, v156
	v_max_f32_e32 v157, v157, v157
	v_max_f32_e32 v158, v158, v158
	v_max_f32_e32 v159, v159, v159
	v_max_f32_e32 v162, v162, v162
	v_max_f32_e32 v163, v163, v163
	v_max_f32_e32 v154, 0x358637bd, v154
	v_max_f32_e32 v155, 0x358637bd, v155
	v_max_f32_e32 v156, 0x358637bd, v156
	v_max_f32_e32 v157, 0x358637bd, v157
	v_max_f32_e32 v158, 0x358637bd, v158
	v_max_f32_e32 v159, 0x358637bd, v159
	v_max_f32_e32 v162, 0x358637bd, v162
	v_max_f32_e32 v163, 0x358637bd, v163
	v_rcp_f32_e32 v154, v154
	v_rcp_f32_e32 v155, v155
	v_rcp_f32_e32 v156, v156
	v_rcp_f32_e32 v157, v157
	v_rcp_f32_e32 v158, v158
	v_rcp_f32_e32 v159, v159
	v_rcp_f32_e32 v162, v162
	v_rcp_f32_e32 v163, v163
	v_lshlrev_b32_e32 v150, 16, v218
	v_and_b32_e32 v151, 0xffff0000, v218
	v_pk_mul_f32 v[150:151], v[154:155], v[150:151]
	s_nop 0
	v_pk_mul_f32 v[88:89], v[88:89], v[150:151]
	v_lshlrev_b32_e32 v150, 16, v220
	v_and_b32_e32 v151, 0xffff0000, v220
	v_pk_mul_f32 v[150:151], v[158:159], v[150:151]
	s_nop 0
	v_pk_mul_f32 v[84:85], v[84:85], v[150:151]
	v_lshlrev_b32_e32 v150, 16, v219
	v_and_b32_e32 v151, 0xffff0000, v219
	v_pk_mul_f32 v[150:151], v[156:157], v[150:151]
	s_nop 0
	v_pk_mul_f32 v[90:91], v[90:91], v[150:151]
	v_lshlrev_b32_e32 v150, 16, v221
	v_and_b32_e32 v151, 0xffff0000, v221
	v_pk_mul_f32 v[150:151], v[162:163], v[150:151]
	s_nop 0
	v_pk_mul_f32 v[86:87], v[86:87], v[150:151]
	s_waitcnt vmcnt(6)
	v_lshlrev_b32_e32 v154, 16, v222
	v_and_b32_e32 v155, 0xffff0000, v222
	v_lshlrev_b32_e32 v156, 16, v223
	v_and_b32_e32 v157, 0xffff0000, v223
	v_lshlrev_b32_e32 v158, 16, v224
	v_and_b32_e32 v159, 0xffff0000, v224
	v_lshlrev_b32_e32 v162, 16, v225
	v_and_b32_e32 v163, 0xffff0000, v225
	v_max_f32_e32 v154, v154, v154
	v_max_f32_e32 v155, v155, v155
	v_max_f32_e32 v156, v156, v156
	v_max_f32_e32 v157, v157, v157
	v_max_f32_e32 v158, v158, v158
	v_max_f32_e32 v159, v159, v159
	v_max_f32_e32 v162, v162, v162
	v_max_f32_e32 v163, v163, v163
	v_max_f32_e32 v154, 0x358637bd, v154
	v_max_f32_e32 v155, 0x358637bd, v155
	v_max_f32_e32 v156, 0x358637bd, v156
	v_max_f32_e32 v157, 0x358637bd, v157
	v_max_f32_e32 v158, 0x358637bd, v158
	v_max_f32_e32 v159, 0x358637bd, v159
	v_max_f32_e32 v162, 0x358637bd, v162
	v_max_f32_e32 v163, 0x358637bd, v163
	v_rcp_f32_e32 v154, v154
	v_rcp_f32_e32 v155, v155
	v_rcp_f32_e32 v156, v156
	v_rcp_f32_e32 v157, v157
	v_rcp_f32_e32 v158, v158
	v_rcp_f32_e32 v159, v159
	v_rcp_f32_e32 v162, v162
	v_rcp_f32_e32 v163, v163
	v_lshlrev_b32_e32 v150, 16, v226
	v_and_b32_e32 v151, 0xffff0000, v226
	v_pk_mul_f32 v[150:151], v[154:155], v[150:151]
	s_nop 0
	v_pk_mul_f32 v[112:113], v[112:113], v[150:151]
	v_lshlrev_b32_e32 v150, 16, v228
	v_and_b32_e32 v151, 0xffff0000, v228
	v_pk_mul_f32 v[150:151], v[158:159], v[150:151]
	s_nop 0
	v_pk_mul_f32 v[108:109], v[108:109], v[150:151]
	v_lshlrev_b32_e32 v150, 16, v227
	v_and_b32_e32 v151, 0xffff0000, v227
	v_pk_mul_f32 v[150:151], v[156:157], v[150:151]
	s_nop 0
	v_pk_mul_f32 v[114:115], v[114:115], v[150:151]
	v_lshlrev_b32_e32 v150, 16, v229
	v_and_b32_e32 v151, 0xffff0000, v229
	v_pk_mul_f32 v[150:151], v[162:163], v[150:151]
	s_nop 0
	v_pk_mul_f32 v[110:111], v[110:111], v[150:151]
	s_waitcnt vmcnt(4)
; __device__ __forceinline__ float bflo(unsigned u) { return __uint_as_float(u << 16); }
; __device__ __forceinline__ float bfhi(unsigned u) { return __uint_as_float(u & 0xffff0000u); }
; __device__ __forceinline__ float frcp(float x) { return __builtin_amdgcn_rcpf(x); }
;     __device__ __forceinline__ void operator()(AccT& acc, const pg8::Unit& u, int wr, int wc, int fr_, int fq_) const {
;     ...
; #pragma unroll
;         for (int ai = 0; ai < 2; ++ai)
; #pragma unroll
;             for (int m = 0; m < 4; ++m) {
;                 const size_t ro = (size_t)(row0 + ai * 128 + m * 16) * D + col0;
; #pragma unroll
;                 for (int bj = 0; bj < 2; ++bj) {
;                     const size_t o = ro + bj * 128;
;                     const u32x4 gb = *(const u32x4*)(GB + o);
;                     f32x4 b0, b1;
;                     b0[0] = fmaxf(bflo(gb[0]), 1e-6f); b0[1] = fmaxf(bfhi(gb[0]), 1e-6f); b0[2] = fmaxf(bflo(gb[1]), 1e-6f); b0[3] = fmaxf(bfhi(gb[1]), 1e-6f);
;                     b1[0] = fmaxf(bflo(gb[2]), 1e-6f); b1[1] = fmaxf(bfhi(gb[2]), 1e-6f); b1[2] = fmaxf(bflo(gb[3]), 1e-6f); b1[3] = fmaxf(bfhi(gb[3]), 1e-6f);
;                     if ((u.sub & 1) == 0) {
;                         const u32x4 ga = *(const u32x4*)(GA + o);
;                         f32x4 a0, a1; a0[0] = bflo(ga[0]); a0[1] = bfhi(ga[0]); a0[2] = bflo(ga[1]); a0[3] = bfhi(ga[1]); a1[0] = bflo(ga[2]); a1[1] = bfhi(ga[2]); a1[2] = bflo(ga[3]); a1[3] = bfhi(ga[3]);
; #pragma unroll
;                         for (int j = 0; j < 4; ++j) { acc[ai][bj][m][0][j] *= a0[j] * frcp(b0[j]); acc[ai][bj][m][1][j] *= a1[j] * frcp(b1[j]); }
	v_lshlrev_b32_e32 v154, 16, v230
	v_and_b32_e32 v155, 0xffff0000, v230
	v_lshlrev_b32_e32 v156, 16, v231
	v_and_b32_e32 v157, 0xffff0000, v231
	v_lshlrev_b32_e32 v158, 16, v232
	v_and_b32_e32 v159, 0xffff0000, v232
	v_lshlrev_b32_e32 v162, 16, v233
	v_and_b32_e32 v163, 0xffff0000, v233
	v_max_f32_e32 v154, v154, v154
	v_max_f32_e32 v155, v155, v155
	v_max_f32_e32 v156, v156, v156
	v_max_f32_e32 v157, v157, v157
	v_max_f32_e32 v158, v158, v158
	v_max_f32_e32 v159, v159, v159
	v_max_f32_e32 v162, v162, v162
	v_max_f32_e32 v163, v163, v163
	v_max_f32_e32 v154, 0x358637bd, v154
	v_max_f32_e32 v155, 0x358637bd, v155
	v_max_f32_e32 v156, 0x358637bd, v156
	v_max_f32_e32 v157, 0x358637bd, v157
	v_max_f32_e32 v158, 0x358637bd, v158
	v_max_f32_e32 v159, 0x358637bd, v159
	v_max_f32_e32 v162, 0x358637bd, v162
	v_max_f32_e32 v163, 0x358637bd, v163
	v_rcp_f32_e32 v154, v154
	v_rcp_f32_e32 v155, v155
	v_rcp_f32_e32 v156, v156
	v_rcp_f32_e32 v157, v157
	v_rcp_f32_e32 v158, v158
	v_rcp_f32_e32 v159, v159
	v_rcp_f32_e32 v162, v162
	v_rcp_f32_e32 v163, v163
	v_lshlrev_b32_e32 v150, 16, v234
	v_and_b32_e32 v151, 0xffff0000, v234
	v_pk_mul_f32 v[150:151], v[154:155], v[150:151]
	s_nop 0
	v_pk_mul_f32 v[80:81], v[80:81], v[150:151]
	v_lshlrev_b32_e32 v150, 16, v236
	v_and_b32_e32 v151, 0xffff0000, v236
	v_pk_mul_f32 v[150:151], v[158:159], v[150:151]
	s_nop 0
	v_pk_mul_f32 v[76:77], v[76:77], v[150:151]
	v_lshlrev_b32_e32 v150, 16, v235
	v_and_b32_e32 v151, 0xffff0000, v235
	v_pk_mul_f32 v[150:151], v[156:157], v[150:151]
	s_nop 0
	v_pk_mul_f32 v[82:83], v[82:83], v[150:151]
	v_lshlrev_b32_e32 v150, 16, v237
	v_and_b32_e32 v151, 0xffff0000, v237
	v_pk_mul_f32 v[150:151], v[162:163], v[150:151]
	s_nop 0
	v_pk_mul_f32 v[78:79], v[78:79], v[150:151]
	s_waitcnt vmcnt(2)
	v_lshlrev_b32_e32 v154, 16, v238
	v_and_b32_e32 v155, 0xffff0000, v238
	v_lshlrev_b32_e32 v156, 16, v239
	v_and_b32_e32 v157, 0xffff0000, v239
	v_lshlrev_b32_e32 v158, 16, v240
	v_and_b32_e32 v159, 0xffff0000, v240
	v_lshlrev_b32_e32 v162, 16, v241
	v_and_b32_e32 v163, 0xffff0000, v241
	v_max_f32_e32 v154, v154, v154
	v_max_f32_e32 v155, v155, v155
	v_max_f32_e32 v156, v156, v156
	v_max_f32_e32 v157, v157, v157
	v_max_f32_e32 v158, v158, v158
	v_max_f32_e32 v159, v159, v159
	v_max_f32_e32 v162, v162, v162
	v_max_f32_e32 v163, v163, v163
	v_max_f32_e32 v154, 0x358637bd, v154
	v_max_f32_e32 v155, 0x358637bd, v155
	v_max_f32_e32 v156, 0x358637bd, v156
	v_max_f32_e32 v157, 0x358637bd, v157
	v_max_f32_e32 v158, 0x358637bd, v158
	v_max_f32_e32 v159, 0x358637bd, v159
	v_max_f32_e32 v162, 0x358637bd, v162
	v_max_f32_e32 v163, 0x358637bd, v163
	v_rcp_f32_e32 v154, v154
	v_rcp_f32_e32 v155, v155
	v_rcp_f32_e32 v156, v156
	v_rcp_f32_e32 v157, v157
	v_rcp_f32_e32 v158, v158
	v_rcp_f32_e32 v159, v159
	v_rcp_f32_e32 v162, v162
	v_rcp_f32_e32 v163, v163
	v_lshlrev_b32_e32 v150, 16, v242
	v_and_b32_e32 v151, 0xffff0000, v242
	v_pk_mul_f32 v[150:151], v[154:155], v[150:151]
	s_nop 0
	v_pk_mul_f32 v[104:105], v[104:105], v[150:151]
	v_lshlrev_b32_e32 v150, 16, v244
	v_and_b32_e32 v151, 0xffff0000, v244
	v_pk_mul_f32 v[150:151], v[158:159], v[150:151]
	s_nop 0
	v_pk_mul_f32 v[100:101], v[100:101], v[150:151]
	v_lshlrev_b32_e32 v150, 16, v243
	v_and_b32_e32 v151, 0xffff0000, v243
	v_pk_mul_f32 v[150:151], v[156:157], v[150:151]
	s_nop 0
	v_pk_mul_f32 v[106:107], v[106:107], v[150:151]
	v_lshlrev_b32_e32 v150, 16, v245
	v_and_b32_e32 v151, 0xffff0000, v245
	v_pk_mul_f32 v[150:151], v[162:163], v[150:151]
	s_nop 0
	v_pk_mul_f32 v[102:103], v[102:103], v[150:151]
	s_waitcnt vmcnt(0)
	v_lshlrev_b32_e32 v154, 16, v246
	v_and_b32_e32 v155, 0xffff0000, v246
	v_lshlrev_b32_e32 v156, 16, v247
	v_and_b32_e32 v157, 0xffff0000, v247
	v_lshlrev_b32_e32 v158, 16, v248
	v_and_b32_e32 v159, 0xffff0000, v248
	v_lshlrev_b32_e32 v162, 16, v249
	v_and_b32_e32 v163, 0xffff0000, v249
	v_max_f32_e32 v154, v154, v154
	v_max_f32_e32 v155, v155, v155
	v_max_f32_e32 v156, v156, v156
	v_max_f32_e32 v157, v157, v157
	v_max_f32_e32 v158, v158, v158
	v_max_f32_e32 v159, v159, v159
	v_max_f32_e32 v162, v162, v162
	v_max_f32_e32 v163, v163, v163
	v_max_f32_e32 v154, 0x358637bd, v154
	v_max_f32_e32 v155, 0x358637bd, v155
	v_max_f32_e32 v156, 0x358637bd, v156
	v_max_f32_e32 v157, 0x358637bd, v157
	v_max_f32_e32 v158, 0x358637bd, v158
	v_max_f32_e32 v159, 0x358637bd, v159
	v_max_f32_e32 v162, 0x358637bd, v162
	v_max_f32_e32 v163, 0x358637bd, v163
	v_rcp_f32_e32 v154, v154
	v_rcp_f32_e32 v155, v155
	v_rcp_f32_e32 v156, v156
	v_rcp_f32_e32 v157, v157
	v_rcp_f32_e32 v158, v158
	v_rcp_f32_e32 v159, v159
	v_rcp_f32_e32 v162, v162
	v_rcp_f32_e32 v163, v163
	v_lshlrev_b32_e32 v150, 16, v250
	v_and_b32_e32 v151, 0xffff0000, v250
	v_pk_mul_f32 v[150:151], v[154:155], v[150:151]
	s_nop 0
	v_pk_mul_f32 v[72:73], v[72:73], v[150:151]
	v_lshlrev_b32_e32 v150, 16, v252
	v_and_b32_e32 v151, 0xffff0000, v252
	v_pk_mul_f32 v[150:151], v[158:159], v[150:151]
	s_nop 0
	v_pk_mul_f32 v[68:69], v[68:69], v[150:151]
	v_lshlrev_b32_e32 v150, 16, v251
	v_and_b32_e32 v151, 0xffff0000, v251
	v_pk_mul_f32 v[150:151], v[156:157], v[150:151]
	s_nop 0
	v_pk_mul_f32 v[74:75], v[74:75], v[150:151]
	v_lshlrev_b32_e32 v150, 16, v253
	v_and_b32_e32 v151, 0xffff0000, v253
	v_pk_mul_f32 v[150:151], v[162:163], v[150:151]
	s_nop 0
	v_pk_mul_f32 v[70:71], v[70:71], v[150:151]
	s_add_u32 s98, s56, 0x40000
	s_addc_u32 s99, s57, 0
	s_add_u32 s100, s54, 0x40000
	s_addc_u32 s101, s55, 0
	global_load_dwordx4 v[190:193], v148, s[98:99]
	global_load_dwordx4 v[194:197], v148, s[100:101]
	global_load_dwordx4 v[198:201], v148, s[98:99] offset:256
	global_load_dwordx4 v[202:205], v148, s[100:101] offset:256
	s_add_u32 s98, s56, 0x48000
	s_addc_u32 s99, s57, 0
	s_add_u32 s100, s54, 0x48000
	s_addc_u32 s101, s55, 0
	global_load_dwordx4 v[206:209], v148, s[98:99]
	global_load_dwordx4 v[210:213], v148, s[100:101]
	global_load_dwordx4 v[214:217], v148, s[98:99] offset:256
	global_load_dwordx4 v[218:221], v148, s[100:101] offset:256
	s_add_u32 s98, s56, 0x50000
	s_addc_u32 s99, s57, 0
	s_add_u32 s100, s54, 0x50000
	s_addc_u32 s101, s55, 0
	global_load_dwordx4 v[222:225], v148, s[98:99]
	global_load_dwordx4 v[226:229], v148, s[100:101]
	global_load_dwordx4 v[230:233], v148, s[98:99] offset:256
	global_load_dwordx4 v[234:237], v148, s[100:101] offset:256
	s_add_u32 s98, s56, 0x58000
	s_addc_u32 s99, s57, 0
	s_add_u32 s100, s54, 0x58000
	s_addc_u32 s101, s55, 0
	global_load_dwordx4 v[238:241], v148, s[98:99]
	global_load_dwordx4 v[242:245], v148, s[100:101]
	global_load_dwordx4 v[246:249], v148, s[98:99] offset:256
	global_load_dwordx4 v[250:253], v148, s[100:101] offset:256
	s_waitcnt vmcnt(14)
; __device__ __forceinline__ float bflo(unsigned u) { return __uint_as_float(u << 16); }
; __device__ __forceinline__ float bfhi(unsigned u) { return __uint_as_float(u & 0xffff0000u); }
; __device__ __forceinline__ float frcp(float x) { return __builtin_amdgcn_rcpf(x); }
;     __device__ __forceinline__ void operator()(AccT& acc, const pg8::Unit& u, int wr, int wc, int fr_, int fq_) const {
;     ...
; #pragma unroll
;         for (int ai = 0; ai < 2; ++ai)
; #pragma unroll
;             for (int m = 0; m < 4; ++m) {
;                 const size_t ro = (size_t)(row0 + ai * 128 + m * 16) * D + col0;
; #pragma unroll
;                 for (int bj = 0; bj < 2; ++bj) {
;                     const size_t o = ro + bj * 128;
;                     const u32x4 gb = *(const u32x4*)(GB + o);
;                     f32x4 b0, b1;
;                     b0[0] = fmaxf(bflo(gb[0]), 1e-6f); b0[1] = fmaxf(bfhi(gb[0]), 1e-6f); b0[2] = fmaxf(bflo(gb[1]), 1e-6f); b0[3] = fmaxf(bfhi(gb[1]), 1e-6f);
;                     b1[0] = fmaxf(bflo(gb[2]), 1e-6f); b1[1] = fmaxf(bfhi(gb[2]), 1e-6f); b1[2] = fmaxf(bflo(gb[3]), 1e-6f); b1[3] = fmaxf(bfhi(gb[3]), 1e-6f);
;                     if ((u.sub & 1) == 0) {
;                         const u32x4 ga = *(const u32x4*)(GA + o);
;                         f32x4 a0, a1; a0[0] = bflo(ga[0]); a0[1] = bfhi(ga[0]); a0[2] = bflo(ga[1]); a0[3] = bfhi(ga[1]); a1[0] = bflo(ga[2]); a1[1] = bfhi(ga[2]); a1[2] = bflo(ga[3]); a1[3] = bfhi(ga[3]);
; #pragma unroll
;                         for (int j = 0; j < 4; ++j) { acc[ai][bj][m][0][j] *= a0[j] * frcp(b0[j]); acc[ai][bj][m][1][j] *= a1[j] * frcp(b1[j]); }
	v_lshlrev_b32_e32 v154, 16, v190
	v_and_b32_e32 v155, 0xffff0000, v190
	v_lshlrev_b32_e32 v156, 16, v191
	v_and_b32_e32 v157, 0xffff0000, v191
	v_lshlrev_b32_e32 v158, 16, v192
	v_and_b32_e32 v159, 0xffff0000, v192
	v_lshlrev_b32_e32 v162, 16, v193
	v_and_b32_e32 v163, 0xffff0000, v193
	v_max_f32_e32 v154, v154, v154
	v_max_f32_e32 v155, v155, v155
	v_max_f32_e32 v156, v156, v156
	v_max_f32_e32 v157, v157, v157
	v_max_f32_e32 v158, v158, v158
	v_max_f32_e32 v159, v159, v159
	v_max_f32_e32 v162, v162, v162
	v_max_f32_e32 v163, v163, v163
	v_max_f32_e32 v154, 0x358637bd, v154
	v_max_f32_e32 v155, 0x358637bd, v155
	v_max_f32_e32 v156, 0x358637bd, v156
	v_max_f32_e32 v157, 0x358637bd, v157
	v_max_f32_e32 v158, 0x358637bd, v158
	v_max_f32_e32 v159, 0x358637bd, v159
	v_max_f32_e32 v162, 0x358637bd, v162
	v_max_f32_e32 v163, 0x358637bd, v163
	v_rcp_f32_e32 v154, v154
	v_rcp_f32_e32 v155, v155
	v_rcp_f32_e32 v156, v156
	v_rcp_f32_e32 v157, v157
	v_rcp_f32_e32 v158, v158
	v_rcp_f32_e32 v159, v159
	v_rcp_f32_e32 v162, v162
	v_rcp_f32_e32 v163, v163
	v_lshlrev_b32_e32 v150, 16, v194
	v_and_b32_e32 v151, 0xffff0000, v194
	v_pk_mul_f32 v[150:151], v[154:155], v[150:151]
	s_nop 0
	v_pk_mul_f32 v[64:65], v[64:65], v[150:151]
	v_lshlrev_b32_e32 v150, 16, v196
	v_and_b32_e32 v151, 0xffff0000, v196
	v_pk_mul_f32 v[150:151], v[158:159], v[150:151]
	s_nop 0
	v_pk_mul_f32 v[60:61], v[60:61], v[150:151]
	v_lshlrev_b32_e32 v150, 16, v195
	v_and_b32_e32 v151, 0xffff0000, v195
	v_pk_mul_f32 v[150:151], v[156:157], v[150:151]
	s_nop 0
	v_pk_mul_f32 v[66:67], v[66:67], v[150:151]
	v_lshlrev_b32_e32 v150, 16, v197
	v_and_b32_e32 v151, 0xffff0000, v197
	v_pk_mul_f32 v[150:151], v[162:163], v[150:151]
	s_nop 0
	v_pk_mul_f32 v[62:63], v[62:63], v[150:151]
	s_waitcnt vmcnt(12)
	v_lshlrev_b32_e32 v154, 16, v198
	v_and_b32_e32 v155, 0xffff0000, v198
	v_lshlrev_b32_e32 v156, 16, v199
	v_and_b32_e32 v157, 0xffff0000, v199
	v_lshlrev_b32_e32 v158, 16, v200
	v_and_b32_e32 v159, 0xffff0000, v200
	v_lshlrev_b32_e32 v162, 16, v201
	v_and_b32_e32 v163, 0xffff0000, v201
	v_max_f32_e32 v154, v154, v154
	v_max_f32_e32 v155, v155, v155
	v_max_f32_e32 v156, v156, v156
	v_max_f32_e32 v157, v157, v157
	v_max_f32_e32 v158, v158, v158
	v_max_f32_e32 v159, v159, v159
	v_max_f32_e32 v162, v162, v162
	v_max_f32_e32 v163, v163, v163
	v_max_f32_e32 v154, 0x358637bd, v154
	v_max_f32_e32 v155, 0x358637bd, v155
	v_max_f32_e32 v156, 0x358637bd, v156
	v_max_f32_e32 v157, 0x358637bd, v157
	v_max_f32_e32 v158, 0x358637bd, v158
	v_max_f32_e32 v159, 0x358637bd, v159
	v_max_f32_e32 v162, 0x358637bd, v162
	v_max_f32_e32 v163, 0x358637bd, v163
	v_rcp_f32_e32 v154, v154
	v_rcp_f32_e32 v155, v155
	v_rcp_f32_e32 v156, v156
	v_rcp_f32_e32 v157, v157
	v_rcp_f32_e32 v158, v158
	v_rcp_f32_e32 v159, v159
	v_rcp_f32_e32 v162, v162
	v_rcp_f32_e32 v163, v163
	v_lshlrev_b32_e32 v150, 16, v202
	v_and_b32_e32 v151, 0xffff0000, v202
	v_pk_mul_f32 v[150:151], v[154:155], v[150:151]
	s_nop 0
	v_pk_mul_f32 v[32:33], v[32:33], v[150:151]
	v_lshlrev_b32_e32 v150, 16, v204
	v_and_b32_e32 v151, 0xffff0000, v204
	v_pk_mul_f32 v[150:151], v[158:159], v[150:151]
	s_nop 0
	v_pk_mul_f32 v[28:29], v[28:29], v[150:151]
	v_lshlrev_b32_e32 v150, 16, v203
	v_and_b32_e32 v151, 0xffff0000, v203
	v_pk_mul_f32 v[150:151], v[156:157], v[150:151]
	s_nop 0
	v_pk_mul_f32 v[34:35], v[34:35], v[150:151]
	v_lshlrev_b32_e32 v150, 16, v205
	v_and_b32_e32 v151, 0xffff0000, v205
	v_pk_mul_f32 v[150:151], v[162:163], v[150:151]
	s_nop 0
	v_pk_mul_f32 v[30:31], v[30:31], v[150:151]
	s_waitcnt vmcnt(10)
	v_lshlrev_b32_e32 v154, 16, v206
	v_and_b32_e32 v155, 0xffff0000, v206
	v_lshlrev_b32_e32 v156, 16, v207
	v_and_b32_e32 v157, 0xffff0000, v207
	v_lshlrev_b32_e32 v158, 16, v208
	v_and_b32_e32 v159, 0xffff0000, v208
	v_lshlrev_b32_e32 v162, 16, v209
	v_and_b32_e32 v163, 0xffff0000, v209
	v_max_f32_e32 v154, v154, v154
	v_max_f32_e32 v155, v155, v155
	v_max_f32_e32 v156, v156, v156
	v_max_f32_e32 v157, v157, v157
	v_max_f32_e32 v158, v158, v158
	v_max_f32_e32 v159, v159, v159
	v_max_f32_e32 v162, v162, v162
	v_max_f32_e32 v163, v163, v163
	v_max_f32_e32 v154, 0x358637bd, v154
	v_max_f32_e32 v155, 0x358637bd, v155
	v_max_f32_e32 v156, 0x358637bd, v156
	v_max_f32_e32 v157, 0x358637bd, v157
	v_max_f32_e32 v158, 0x358637bd, v158
	v_max_f32_e32 v159, 0x358637bd, v159
	v_max_f32_e32 v162, 0x358637bd, v162
	v_max_f32_e32 v163, 0x358637bd, v163
	v_rcp_f32_e32 v154, v154
	v_rcp_f32_e32 v155, v155
	v_rcp_f32_e32 v156, v156
	v_rcp_f32_e32 v157, v157
	v_rcp_f32_e32 v158, v158
	v_rcp_f32_e32 v159, v159
	v_rcp_f32_e32 v162, v162
	v_rcp_f32_e32 v163, v163
	v_lshlrev_b32_e32 v150, 16, v210
	v_and_b32_e32 v151, 0xffff0000, v210
	v_pk_mul_f32 v[150:151], v[154:155], v[150:151]
	s_nop 0
	v_pk_mul_f32 v[56:57], v[56:57], v[150:151]
	v_lshlrev_b32_e32 v150, 16, v212
	v_and_b32_e32 v151, 0xffff0000, v212
	v_pk_mul_f32 v[150:151], v[158:159], v[150:151]
	s_nop 0
	v_pk_mul_f32 v[52:53], v[52:53], v[150:151]
	v_lshlrev_b32_e32 v150, 16, v211
	v_and_b32_e32 v151, 0xffff0000, v211
	v_pk_mul_f32 v[150:151], v[156:157], v[150:151]
	s_nop 0
	v_pk_mul_f32 v[58:59], v[58:59], v[150:151]
	v_lshlrev_b32_e32 v150, 16, v213
	v_and_b32_e32 v151, 0xffff0000, v213
	v_pk_mul_f32 v[150:151], v[162:163], v[150:151]
	s_nop 0
	v_pk_mul_f32 v[54:55], v[54:55], v[150:151]
	s_waitcnt vmcnt(8)
; __device__ __forceinline__ float bflo(unsigned u) { return __uint_as_float(u << 16); }
; __device__ __forceinline__ float bfhi(unsigned u) { return __uint_as_float(u & 0xffff0000u); }
; __device__ __forceinline__ float frcp(float x) { return __builtin_amdgcn_rcpf(x); }
;     __device__ __forceinline__ void operator()(AccT& acc, const pg8::Unit& u, int wr, int wc, int fr_, int fq_) const {
;     ...
;                     const u32x4 gb = *(const u32x4*)(GB + o);
;                     f32x4 b0, b1;
;                     b0[0] = fmaxf(bflo(gb[0]), 1e-6f); b0[1] = fmaxf(bfhi(gb[0]), 1e-6f); b0[2] = fmaxf(bflo(gb[1]), 1e-6f); b0[3] = fmaxf(bfhi(gb[1]), 1e-6f);
;                     b1[0] = fmaxf(bflo(gb[2]), 1e-6f); b1[1] = fmaxf(bfhi(gb[2]), 1e-6f); b1[2] = fmaxf(bflo(gb[3]), 1e-6f); b1[3] = fmaxf(bfhi(gb[3]), 1e-6f);
;                     if ((u.sub & 1) == 0) {
;                         const u32x4 ga = *(const u32x4*)(GA + o);
;                         f32x4 a0, a1; a0[0] = bflo(ga[0]); a0[1] = bfhi(ga[0]); a0[2] = bflo(ga[1]); a0[3] = bfhi(ga[1]); a1[0] = bflo(ga[2]); a1[1] = bfhi(ga[2]); a1[2] = bflo(ga[3]); a1[3] = bfhi(ga[3]);
; #pragma unroll
;                         for (int j = 0; j < 4; ++j) { acc[ai][bj][m][0][j] *= a0[j] * frcp(b0[j]); acc[ai][bj][m][1][j] *= a1[j] * frcp(b1[j]); }
	v_lshlrev_b32_e32 v154, 16, v214
	v_and_b32_e32 v155, 0xffff0000, v214
	v_lshlrev_b32_e32 v156, 16, v215
	v_and_b32_e32 v157, 0xffff0000, v215
	v_lshlrev_b32_e32 v158, 16, v216
	v_and_b32_e32 v159, 0xffff0000, v216
	v_lshlrev_b32_e32 v162, 16, v217
	v_and_b32_e32 v163, 0xffff0000, v217
	v_max_f32_e32 v154, v154, v154
	v_max_f32_e32 v155, v155, v155
	v_max_f32_e32 v156, v156, v156
	v_max_f32_e32 v157, v157, v157
	v_max_f32_e32 v158, v158, v158
	v_max_f32_e32 v159, v159, v159
	v_max_f32_e32 v162, v162, v162
	v_max_f32_e32 v163, v163, v163
	v_max_f32_e32 v154, 0x358637bd, v154
	v_max_f32_e32 v155, 0x358637bd, v155
	v_max_f32_e32 v156, 0x358637bd, v156
	v_max_f32_e32 v157, 0x358637bd, v157
	v_max_f32_e32 v158, 0x358637bd, v158
	v_max_f32_e32 v159, 0x358637bd, v159
	v_max_f32_e32 v162, 0x358637bd, v162
	v_max_f32_e32 v163, 0x358637bd, v163
	v_rcp_f32_e32 v154, v154
	v_rcp_f32_e32 v155, v155
	v_rcp_f32_e32 v156, v156
	v_rcp_f32_e32 v157, v157
	v_rcp_f32_e32 v158, v158
	v_rcp_f32_e32 v159, v159
	v_rcp_f32_e32 v162, v162
	v_rcp_f32_e32 v163, v163
	v_lshlrev_b32_e32 v150, 16, v218
	v_and_b32_e32 v151, 0xffff0000, v218
	v_pk_mul_f32 v[150:151], v[154:155], v[150:151]
	s_nop 0
	v_pk_mul_f32 v[24:25], v[24:25], v[150:151]
	v_lshlrev_b32_e32 v150, 16, v220
	v_and_b32_e32 v151, 0xffff0000, v220
	v_pk_mul_f32 v[150:151], v[158:159], v[150:151]
	s_nop 0
	v_pk_mul_f32 v[20:21], v[20:21], v[150:151]
	v_lshlrev_b32_e32 v150, 16, v219
	v_and_b32_e32 v151, 0xffff0000, v219
	v_pk_mul_f32 v[150:151], v[156:157], v[150:151]
	s_nop 0
	v_pk_mul_f32 v[26:27], v[26:27], v[150:151]
	v_lshlrev_b32_e32 v150, 16, v221
	v_and_b32_e32 v151, 0xffff0000, v221
	v_pk_mul_f32 v[150:151], v[162:163], v[150:151]
	s_nop 0
	v_pk_mul_f32 v[22:23], v[22:23], v[150:151]
	s_waitcnt vmcnt(6)
	v_lshlrev_b32_e32 v154, 16, v222
	v_and_b32_e32 v155, 0xffff0000, v222
	v_lshlrev_b32_e32 v156, 16, v223
	v_and_b32_e32 v157, 0xffff0000, v223
	v_lshlrev_b32_e32 v158, 16, v224
	v_and_b32_e32 v159, 0xffff0000, v224
	v_lshlrev_b32_e32 v162, 16, v225
	v_and_b32_e32 v163, 0xffff0000, v225
	v_max_f32_e32 v154, v154, v154
	v_max_f32_e32 v155, v155, v155
	v_max_f32_e32 v156, v156, v156
	v_max_f32_e32 v157, v157, v157
	v_max_f32_e32 v158, v158, v158
	v_max_f32_e32 v159, v159, v159
	v_max_f32_e32 v162, v162, v162
	v_max_f32_e32 v163, v163, v163
	v_max_f32_e32 v154, 0x358637bd, v154
	v_max_f32_e32 v155, 0x358637bd, v155
	v_max_f32_e32 v156, 0x358637bd, v156
	v_max_f32_e32 v157, 0x358637bd, v157
	v_max_f32_e32 v158, 0x358637bd, v158
	v_max_f32_e32 v159, 0x358637bd, v159
	v_max_f32_e32 v162, 0x358637bd, v162
	v_max_f32_e32 v163, 0x358637bd, v163
	v_rcp_f32_e32 v154, v154
	v_rcp_f32_e32 v155, v155
	v_rcp_f32_e32 v156, v156
	v_rcp_f32_e32 v157, v157
	v_rcp_f32_e32 v158, v158
	v_rcp_f32_e32 v159, v159
	v_rcp_f32_e32 v162, v162
	v_rcp_f32_e32 v163, v163
	v_lshlrev_b32_e32 v150, 16, v226
	v_and_b32_e32 v151, 0xffff0000, v226
	v_pk_mul_f32 v[150:151], v[154:155], v[150:151]
	s_nop 0
	v_pk_mul_f32 v[48:49], v[48:49], v[150:151]
	v_lshlrev_b32_e32 v150, 16, v228
	v_and_b32_e32 v151, 0xffff0000, v228
	v_pk_mul_f32 v[150:151], v[158:159], v[150:151]
	s_nop 0
	v_pk_mul_f32 v[44:45], v[44:45], v[150:151]
	v_lshlrev_b32_e32 v150, 16, v227
	v_and_b32_e32 v151, 0xffff0000, v227
	v_pk_mul_f32 v[150:151], v[156:157], v[150:151]
	s_nop 0
	v_pk_mul_f32 v[50:51], v[50:51], v[150:151]
	v_lshlrev_b32_e32 v150, 16, v229
	v_and_b32_e32 v151, 0xffff0000, v229
	v_pk_mul_f32 v[150:151], v[162:163], v[150:151]
	s_nop 0
	v_pk_mul_f32 v[46:47], v[46:47], v[150:151]
	s_waitcnt vmcnt(4)
	v_lshlrev_b32_e32 v154, 16, v230
	v_and_b32_e32 v155, 0xffff0000, v230
	v_lshlrev_b32_e32 v156, 16, v231
	v_and_b32_e32 v157, 0xffff0000, v231
	v_lshlrev_b32_e32 v158, 16, v232
	v_and_b32_e32 v159, 0xffff0000, v232
	v_lshlrev_b32_e32 v162, 16, v233
	v_and_b32_e32 v163, 0xffff0000, v233
	v_max_f32_e32 v154, v154, v154
	v_max_f32_e32 v155, v155, v155
	v_max_f32_e32 v156, v156, v156
	v_max_f32_e32 v157, v157, v157
	v_max_f32_e32 v158, v158, v158
	v_max_f32_e32 v159, v159, v159
	v_max_f32_e32 v162, v162, v162
	v_max_f32_e32 v163, v163, v163
	v_max_f32_e32 v154, 0x358637bd, v154
	v_max_f32_e32 v155, 0x358637bd, v155
	v_max_f32_e32 v156, 0x358637bd, v156
	v_max_f32_e32 v157, 0x358637bd, v157
	v_max_f32_e32 v158, 0x358637bd, v158
	v_max_f32_e32 v159, 0x358637bd, v159
	v_max_f32_e32 v162, 0x358637bd, v162
	v_max_f32_e32 v163, 0x358637bd, v163
	v_rcp_f32_e32 v154, v154
	v_rcp_f32_e32 v155, v155
	v_rcp_f32_e32 v156, v156
	v_rcp_f32_e32 v157, v157
	v_rcp_f32_e32 v158, v158
	v_rcp_f32_e32 v159, v159
	v_rcp_f32_e32 v162, v162
	v_rcp_f32_e32 v163, v163
	v_lshlrev_b32_e32 v150, 16, v234
	v_and_b32_e32 v151, 0xffff0000, v234
	v_pk_mul_f32 v[150:151], v[154:155], v[150:151]
	s_nop 0
	v_pk_mul_f32 v[16:17], v[16:17], v[150:151]
	v_lshlrev_b32_e32 v150, 16, v236
	v_and_b32_e32 v151, 0xffff0000, v236
	v_pk_mul_f32 v[150:151], v[158:159], v[150:151]
	s_nop 0
	v_pk_mul_f32 v[12:13], v[12:13], v[150:151]
	v_lshlrev_b32_e32 v150, 16, v235
	v_and_b32_e32 v151, 0xffff0000, v235
	v_pk_mul_f32 v[150:151], v[156:157], v[150:151]
	s_nop 0
	v_pk_mul_f32 v[18:19], v[18:19], v[150:151]
	v_lshlrev_b32_e32 v150, 16, v237
	v_and_b32_e32 v151, 0xffff0000, v237
	v_pk_mul_f32 v[150:151], v[162:163], v[150:151]
	s_nop 0
	v_pk_mul_f32 v[14:15], v[14:15], v[150:151]
	s_waitcnt vmcnt(2)
; __device__ __forceinline__ unsigned pk2(float lo, float hi) { const f32x2_t v = {lo, hi}; const bf16v2_t b = __builtin_convertvector(v, bf16v2_t); return __builtin_bit_cast(unsigned, b); }
; __device__ __forceinline__ float bflo(unsigned u) { return __uint_as_float(u << 16); }
; __device__ __forceinline__ float bfhi(unsigned u) { return __uint_as_float(u & 0xffff0000u); }
; __device__ __forceinline__ float frcp(float x) { return __builtin_amdgcn_rcpf(x); }
;     __device__ __forceinline__ void operator()(AccT& acc, const pg8::Unit& u, int wr, int wc, int fr_, int fq_) const {
;     ...
;                     const u32x4 gb = *(const u32x4*)(GB + o);
;                     f32x4 b0, b1;
;                     b0[0] = fmaxf(bflo(gb[0]), 1e-6f); b0[1] = fmaxf(bfhi(gb[0]), 1e-6f); b0[2] = fmaxf(bflo(gb[1]), 1e-6f); b0[3] = fmaxf(bfhi(gb[1]), 1e-6f);
;                     b1[0] = fmaxf(bflo(gb[2]), 1e-6f); b1[1] = fmaxf(bfhi(gb[2]), 1e-6f); b1[2] = fmaxf(bflo(gb[3]), 1e-6f); b1[3] = fmaxf(bfhi(gb[3]), 1e-6f);
;                     if ((u.sub & 1) == 0) {
;                         const u32x4 ga = *(const u32x4*)(GA + o);
;                         f32x4 a0, a1; a0[0] = bflo(ga[0]); a0[1] = bfhi(ga[0]); a0[2] = bflo(ga[1]); a0[3] = bfhi(ga[1]); a1[0] = bflo(ga[2]); a1[1] = bfhi(ga[2]); a1[2] = bflo(ga[3]); a1[3] = bfhi(ga[3]);
; #pragma unroll
;                         for (int j = 0; j < 4; ++j) { acc[ai][bj][m][0][j] *= a0[j] * frcp(b0[j]); acc[ai][bj][m][1][j] *= a1[j] * frcp(b1[j]); }
;                     } else {
;                         const f32x4 t0 = b0 * acc[ai][bj][m][0], t1 = b1 * acc[ai][bj][m][1];
;                         u32x4 w; w[0] = pk2(t0[0], t0[1]); w[1] = pk2(t0[2], t0[3]); w[2] = pk2(t1[0], t1[1]); w[3] = pk2(t1[2], t1[3]);
;                         *(u32x4*)(MB + o) = w;
	v_lshlrev_b32_e32 v154, 16, v238
	v_and_b32_e32 v155, 0xffff0000, v238
	v_lshlrev_b32_e32 v156, 16, v239
	v_and_b32_e32 v157, 0xffff0000, v239
	v_lshlrev_b32_e32 v158, 16, v240
	v_and_b32_e32 v159, 0xffff0000, v240
	v_lshlrev_b32_e32 v162, 16, v241
	v_and_b32_e32 v163, 0xffff0000, v241
	v_max_f32_e32 v154, v154, v154
	v_max_f32_e32 v155, v155, v155
	v_max_f32_e32 v156, v156, v156
	v_max_f32_e32 v157, v157, v157
	v_max_f32_e32 v158, v158, v158
	v_max_f32_e32 v159, v159, v159
	v_max_f32_e32 v162, v162, v162
	v_max_f32_e32 v163, v163, v163
	v_max_f32_e32 v154, 0x358637bd, v154
	v_max_f32_e32 v155, 0x358637bd, v155
	v_max_f32_e32 v156, 0x358637bd, v156
	v_max_f32_e32 v157, 0x358637bd, v157
	v_max_f32_e32 v158, 0x358637bd, v158
	v_max_f32_e32 v159, 0x358637bd, v159
	v_max_f32_e32 v162, 0x358637bd, v162
	v_max_f32_e32 v163, 0x358637bd, v163
	v_rcp_f32_e32 v154, v154
	v_rcp_f32_e32 v155, v155
	v_rcp_f32_e32 v156, v156
	v_rcp_f32_e32 v157, v157
	v_rcp_f32_e32 v158, v158
	v_rcp_f32_e32 v159, v159
	v_rcp_f32_e32 v162, v162
	v_rcp_f32_e32 v163, v163
	v_lshlrev_b32_e32 v150, 16, v242
	v_and_b32_e32 v151, 0xffff0000, v242
	v_pk_mul_f32 v[150:151], v[154:155], v[150:151]
	s_nop 0
	v_pk_mul_f32 v[40:41], v[40:41], v[150:151]
	v_lshlrev_b32_e32 v150, 16, v244
	v_and_b32_e32 v151, 0xffff0000, v244
	v_pk_mul_f32 v[150:151], v[158:159], v[150:151]
	s_nop 0
	v_pk_mul_f32 v[36:37], v[36:37], v[150:151]
	v_lshlrev_b32_e32 v150, 16, v243
	v_and_b32_e32 v151, 0xffff0000, v243
	v_pk_mul_f32 v[150:151], v[156:157], v[150:151]
	s_nop 0
	v_pk_mul_f32 v[42:43], v[42:43], v[150:151]
	v_lshlrev_b32_e32 v150, 16, v245
	v_and_b32_e32 v151, 0xffff0000, v245
	v_pk_mul_f32 v[150:151], v[162:163], v[150:151]
	s_nop 0
	v_pk_mul_f32 v[38:39], v[38:39], v[150:151]
	s_waitcnt vmcnt(0)
	v_lshlrev_b32_e32 v154, 16, v246
	v_and_b32_e32 v155, 0xffff0000, v246
	v_lshlrev_b32_e32 v156, 16, v247
	v_and_b32_e32 v157, 0xffff0000, v247
	v_lshlrev_b32_e32 v158, 16, v248
	v_and_b32_e32 v159, 0xffff0000, v248
	v_lshlrev_b32_e32 v162, 16, v249
	v_and_b32_e32 v163, 0xffff0000, v249
	v_max_f32_e32 v154, v154, v154
	v_max_f32_e32 v155, v155, v155
	v_max_f32_e32 v156, v156, v156
	v_max_f32_e32 v157, v157, v157
	v_max_f32_e32 v158, v158, v158
	v_max_f32_e32 v159, v159, v159
	v_max_f32_e32 v162, v162, v162
	v_max_f32_e32 v163, v163, v163
	v_max_f32_e32 v154, 0x358637bd, v154
	v_max_f32_e32 v155, 0x358637bd, v155
	v_max_f32_e32 v156, 0x358637bd, v156
	v_max_f32_e32 v157, 0x358637bd, v157
	v_max_f32_e32 v158, 0x358637bd, v158
	v_max_f32_e32 v159, 0x358637bd, v159
	v_max_f32_e32 v162, 0x358637bd, v162
	v_max_f32_e32 v163, 0x358637bd, v163
	v_rcp_f32_e32 v154, v154
	v_rcp_f32_e32 v155, v155
	v_rcp_f32_e32 v156, v156
	v_rcp_f32_e32 v157, v157
	v_rcp_f32_e32 v158, v158
	v_rcp_f32_e32 v159, v159
	v_rcp_f32_e32 v162, v162
	v_rcp_f32_e32 v163, v163
	v_lshlrev_b32_e32 v150, 16, v250
	v_and_b32_e32 v151, 0xffff0000, v250
	v_pk_mul_f32 v[150:151], v[154:155], v[150:151]
	s_nop 0
	v_pk_mul_f32 v[8:9], v[8:9], v[150:151]
	v_lshlrev_b32_e32 v150, 16, v252
	v_and_b32_e32 v151, 0xffff0000, v252
	v_pk_mul_f32 v[150:151], v[158:159], v[150:151]
	s_nop 0
	v_pk_mul_f32 v[4:5], v[4:5], v[150:151]
	v_lshlrev_b32_e32 v150, 16, v251
	v_and_b32_e32 v151, 0xffff0000, v251
	v_pk_mul_f32 v[150:151], v[156:157], v[150:151]
	s_nop 0
	v_pk_mul_f32 v[10:11], v[10:11], v[150:151]
	v_lshlrev_b32_e32 v150, 16, v253
	v_and_b32_e32 v151, 0xffff0000, v253
	v_pk_mul_f32 v[150:151], v[162:163], v[150:151]
	s_nop 0
	v_pk_mul_f32 v[6:7], v[6:7], v[150:151]
	s_branch .LBB0_543
.Lmg_sub1:
	s_mov_b32 s98, s56
	s_mov_b32 s99, s57
	global_load_dwordx4 v[190:193], v148, s[98:99]
	global_load_dwordx4 v[194:197], v148, s[98:99] offset:256
	s_add_u32 s98, s56, 0x8000
	s_addc_u32 s99, s57, 0
	global_load_dwordx4 v[198:201], v148, s[98:99]
	global_load_dwordx4 v[202:205], v148, s[98:99] offset:256
	s_add_u32 s98, s56, 0x10000
	s_addc_u32 s99, s57, 0
	global_load_dwordx4 v[206:209], v148, s[98:99]
	global_load_dwordx4 v[210:213], v148, s[98:99] offset:256
	s_add_u32 s98, s56, 0x18000
	s_addc_u32 s99, s57, 0
	global_load_dwordx4 v[214:217], v148, s[98:99]
	global_load_dwordx4 v[218:221], v148, s[98:99] offset:256
	s_add_u32 s98, s56, 0x40000
	s_addc_u32 s99, s57, 0
	global_load_dwordx4 v[222:225], v148, s[98:99]
	global_load_dwordx4 v[226:229], v148, s[98:99] offset:256
	s_add_u32 s98, s56, 0x48000
	s_addc_u32 s99, s57, 0
	global_load_dwordx4 v[230:233], v148, s[98:99]
	global_load_dwordx4 v[234:237], v148, s[98:99] offset:256
	s_add_u32 s98, s56, 0x50000
	s_addc_u32 s99, s57, 0
	global_load_dwordx4 v[238:241], v148, s[98:99]
	global_load_dwordx4 v[242:245], v148, s[98:99] offset:256
	s_add_u32 s98, s56, 0x58000
	s_addc_u32 s99, s57, 0
	global_load_dwordx4 v[246:249], v148, s[98:99]
	global_load_dwordx4 v[250:253], v148, s[98:99] offset:256
	s_waitcnt vmcnt(15)
	v_lshlrev_b32_e32 v154, 16, v190
	v_and_b32_e32 v155, 0xffff0000, v190
	v_lshlrev_b32_e32 v156, 16, v191
	v_and_b32_e32 v157, 0xffff0000, v191
	v_lshlrev_b32_e32 v158, 16, v192
	v_and_b32_e32 v159, 0xffff0000, v192
	v_lshlrev_b32_e32 v162, 16, v193
	v_and_b32_e32 v163, 0xffff0000, v193
	v_max_f32_e32 v154, v154, v154
	v_max_f32_e32 v155, v155, v155
	v_max_f32_e32 v156, v156, v156
	v_max_f32_e32 v157, v157, v157
	v_max_f32_e32 v158, v158, v158
	v_max_f32_e32 v159, v159, v159
	v_max_f32_e32 v162, v162, v162
	v_max_f32_e32 v163, v163, v163
	v_max_f32_e32 v154, 0x358637bd, v154
	v_max_f32_e32 v155, 0x358637bd, v155
	v_max_f32_e32 v156, 0x358637bd, v156
	v_max_f32_e32 v157, 0x358637bd, v157
	v_max_f32_e32 v158, 0x358637bd, v158
	v_max_f32_e32 v159, 0x358637bd, v159
	v_max_f32_e32 v162, 0x358637bd, v162
	v_max_f32_e32 v163, 0x358637bd, v163
	v_pk_mul_f32 v[128:129], v[128:129], v[154:155]
	v_pk_mul_f32 v[130:131], v[130:131], v[156:157]
	v_pk_mul_f32 v[124:125], v[124:125], v[158:159]
	v_pk_mul_f32 v[126:127], v[126:127], v[162:163]
	v_cvt_pk_bf16_f32 v128, v128, v129
	v_cvt_pk_bf16_f32 v129, v130, v131
	v_cvt_pk_bf16_f32 v130, v124, v125
	v_cvt_pk_bf16_f32 v131, v126, v127
	s_mov_b32 s100, s50
	s_mov_b32 s101, s51
	global_store_dwordx4 v148, v[128:131], s[100:101]
	s_waitcnt vmcnt(15)
; __device__ __forceinline__ unsigned pk2(float lo, float hi) { const f32x2_t v = {lo, hi}; const bf16v2_t b = __builtin_convertvector(v, bf16v2_t); return __builtin_bit_cast(unsigned, b); }
;     __device__ __forceinline__ void operator()(AccT& acc, const pg8::Unit& u, int wr, int wc, int fr_, int fq_) const {
;     ...
;                         const f32x4 t0 = b0 * acc[ai][bj][m][0], t1 = b1 * acc[ai][bj][m][1];
;                         u32x4 w; w[0] = pk2(t0[0], t0[1]); w[1] = pk2(t0[2], t0[3]); w[2] = pk2(t1[0], t1[1]); w[3] = pk2(t1[2], t1[3]);
;                         *(u32x4*)(MB + o) = w;
	v_lshlrev_b32_e32 v154, 16, v194
	v_and_b32_e32 v155, 0xffff0000, v194
	v_lshlrev_b32_e32 v156, 16, v195
	v_and_b32_e32 v157, 0xffff0000, v195
	v_lshlrev_b32_e32 v158, 16, v196
	v_and_b32_e32 v159, 0xffff0000, v196
	v_lshlrev_b32_e32 v162, 16, v197
	v_and_b32_e32 v163, 0xffff0000, v197
	v_max_f32_e32 v154, v154, v154
	v_max_f32_e32 v155, v155, v155
	v_max_f32_e32 v156, v156, v156
	v_max_f32_e32 v157, v157, v157
	v_max_f32_e32 v158, v158, v158
	v_max_f32_e32 v159, v159, v159
	v_max_f32_e32 v162, v162, v162
	v_max_f32_e32 v163, v163, v163
	v_max_f32_e32 v154, 0x358637bd, v154
	v_max_f32_e32 v155, 0x358637bd, v155
	v_max_f32_e32 v156, 0x358637bd, v156
	v_max_f32_e32 v157, 0x358637bd, v157
	v_max_f32_e32 v158, 0x358637bd, v158
	v_max_f32_e32 v159, 0x358637bd, v159
	v_max_f32_e32 v162, 0x358637bd, v162
	v_max_f32_e32 v163, 0x358637bd, v163
	v_pk_mul_f32 v[96:97], v[96:97], v[154:155]
	v_pk_mul_f32 v[98:99], v[98:99], v[156:157]
	v_pk_mul_f32 v[92:93], v[92:93], v[158:159]
	v_pk_mul_f32 v[94:95], v[94:95], v[162:163]
	v_cvt_pk_bf16_f32 v96, v96, v97
	v_cvt_pk_bf16_f32 v97, v98, v99
	v_cvt_pk_bf16_f32 v98, v92, v93
	v_cvt_pk_bf16_f32 v99, v94, v95
	global_store_dwordx4 v148, v[96:99], s[100:101] offset:256
	s_waitcnt vmcnt(15)
	v_lshlrev_b32_e32 v154, 16, v198
	v_and_b32_e32 v155, 0xffff0000, v198
	v_lshlrev_b32_e32 v156, 16, v199
	v_and_b32_e32 v157, 0xffff0000, v199
	v_lshlrev_b32_e32 v158, 16, v200
	v_and_b32_e32 v159, 0xffff0000, v200
	v_lshlrev_b32_e32 v162, 16, v201
	v_and_b32_e32 v163, 0xffff0000, v201
	v_max_f32_e32 v154, v154, v154
	v_max_f32_e32 v155, v155, v155
	v_max_f32_e32 v156, v156, v156
	v_max_f32_e32 v157, v157, v157
	v_max_f32_e32 v158, v158, v158
	v_max_f32_e32 v159, v159, v159
	v_max_f32_e32 v162, v162, v162
	v_max_f32_e32 v163, v163, v163
	v_max_f32_e32 v154, 0x358637bd, v154
	v_max_f32_e32 v155, 0x358637bd, v155
	v_max_f32_e32 v156, 0x358637bd, v156
	v_max_f32_e32 v157, 0x358637bd, v157
	v_max_f32_e32 v158, 0x358637bd, v158
	v_max_f32_e32 v159, 0x358637bd, v159
	v_max_f32_e32 v162, 0x358637bd, v162
	v_max_f32_e32 v163, 0x358637bd, v163
	v_pk_mul_f32 v[120:121], v[120:121], v[154:155]
	v_pk_mul_f32 v[122:123], v[122:123], v[156:157]
	v_pk_mul_f32 v[116:117], v[116:117], v[158:159]
	v_pk_mul_f32 v[118:119], v[118:119], v[162:163]
	v_cvt_pk_bf16_f32 v120, v120, v121
	v_cvt_pk_bf16_f32 v121, v122, v123
	v_cvt_pk_bf16_f32 v122, v116, v117
	v_cvt_pk_bf16_f32 v123, v118, v119
	s_add_u32 s100, s50, 0x8000
	s_addc_u32 s101, s51, 0
	global_store_dwordx4 v148, v[120:123], s[100:101]
	s_waitcnt vmcnt(15)
	v_lshlrev_b32_e32 v154, 16, v202
	v_and_b32_e32 v155, 0xffff0000, v202
	v_lshlrev_b32_e32 v156, 16, v203
	v_and_b32_e32 v157, 0xffff0000, v203
	v_lshlrev_b32_e32 v158, 16, v204
	v_and_b32_e32 v159, 0xffff0000, v204
	v_lshlrev_b32_e32 v162, 16, v205
	v_and_b32_e32 v163, 0xffff0000, v205
	v_max_f32_e32 v154, v154, v154
	v_max_f32_e32 v155, v155, v155
	v_max_f32_e32 v156, v156, v156
	v_max_f32_e32 v157, v157, v157
	v_max_f32_e32 v158, v158, v158
	v_max_f32_e32 v159, v159, v159
	v_max_f32_e32 v162, v162, v162
	v_max_f32_e32 v163, v163, v163
	v_max_f32_e32 v154, 0x358637bd, v154
	v_max_f32_e32 v155, 0x358637bd, v155
	v_max_f32_e32 v156, 0x358637bd, v156
	v_max_f32_e32 v157, 0x358637bd, v157
	v_max_f32_e32 v158, 0x358637bd, v158
	v_max_f32_e32 v159, 0x358637bd, v159
	v_max_f32_e32 v162, 0x358637bd, v162
	v_max_f32_e32 v163, 0x358637bd, v163
	v_pk_mul_f32 v[88:89], v[88:89], v[154:155]
	v_pk_mul_f32 v[90:91], v[90:91], v[156:157]
	v_pk_mul_f32 v[84:85], v[84:85], v[158:159]
	v_pk_mul_f32 v[86:87], v[86:87], v[162:163]
	v_cvt_pk_bf16_f32 v88, v88, v89
	v_cvt_pk_bf16_f32 v89, v90, v91
	v_cvt_pk_bf16_f32 v90, v84, v85
	v_cvt_pk_bf16_f32 v91, v86, v87
	global_store_dwordx4 v148, v[88:91], s[100:101] offset:256
	s_waitcnt vmcnt(15)
	v_lshlrev_b32_e32 v154, 16, v206
	v_and_b32_e32 v155, 0xffff0000, v206
	v_lshlrev_b32_e32 v156, 16, v207
	v_and_b32_e32 v157, 0xffff0000, v207
	v_lshlrev_b32_e32 v158, 16, v208
	v_and_b32_e32 v159, 0xffff0000, v208
	v_lshlrev_b32_e32 v162, 16, v209
	v_and_b32_e32 v163, 0xffff0000, v209
	v_max_f32_e32 v154, v154, v154
	v_max_f32_e32 v155, v155, v155
	v_max_f32_e32 v156, v156, v156
	v_max_f32_e32 v157, v157, v157
	v_max_f32_e32 v158, v158, v158
	v_max_f32_e32 v159, v159, v159
	v_max_f32_e32 v162, v162, v162
	v_max_f32_e32 v163, v163, v163
	v_max_f32_e32 v154, 0x358637bd, v154
	v_max_f32_e32 v155, 0x358637bd, v155
	v_max_f32_e32 v156, 0x358637bd, v156
	v_max_f32_e32 v157, 0x358637bd, v157
	v_max_f32_e32 v158, 0x358637bd, v158
	v_max_f32_e32 v159, 0x358637bd, v159
	v_max_f32_e32 v162, 0x358637bd, v162
	v_max_f32_e32 v163, 0x358637bd, v163
	v_pk_mul_f32 v[112:113], v[112:113], v[154:155]
	v_pk_mul_f32 v[114:115], v[114:115], v[156:157]
	v_pk_mul_f32 v[108:109], v[108:109], v[158:159]
	v_pk_mul_f32 v[110:111], v[110:111], v[162:163]
	v_cvt_pk_bf16_f32 v112, v112, v113
	v_cvt_pk_bf16_f32 v113, v114, v115
	v_cvt_pk_bf16_f32 v114, v108, v109
	v_cvt_pk_bf16_f32 v115, v110, v111
	s_add_u32 s100, s50, 0x10000
	s_addc_u32 s101, s51, 0
	global_store_dwordx4 v148, v[112:115], s[100:101]
	s_waitcnt vmcnt(15)
; __device__ __forceinline__ unsigned pk2(float lo, float hi) { const f32x2_t v = {lo, hi}; const bf16v2_t b = __builtin_convertvector(v, bf16v2_t); return __builtin_bit_cast(unsigned, b); }
;     __device__ __forceinline__ void operator()(AccT& acc, const pg8::Unit& u, int wr, int wc, int fr_, int fq_) const {
;     ...
;                         const f32x4 t0 = b0 * acc[ai][bj][m][0], t1 = b1 * acc[ai][bj][m][1];
;                         u32x4 w; w[0] = pk2(t0[0], t0[1]); w[1] = pk2(t0[2], t0[3]); w[2] = pk2(t1[0], t1[1]); w[3] = pk2(t1[2], t1[3]);
;                         *(u32x4*)(MB + o) = w;
	v_lshlrev_b32_e32 v154, 16, v210
	v_and_b32_e32 v155, 0xffff0000, v210
	v_lshlrev_b32_e32 v156, 16, v211
	v_and_b32_e32 v157, 0xffff0000, v211
	v_lshlrev_b32_e32 v158, 16, v212
	v_and_b32_e32 v159, 0xffff0000, v212
	v_lshlrev_b32_e32 v162, 16, v213
	v_and_b32_e32 v163, 0xffff0000, v213
	v_max_f32_e32 v154, v154, v154
	v_max_f32_e32 v155, v155, v155
	v_max_f32_e32 v156, v156, v156
	v_max_f32_e32 v157, v157, v157
	v_max_f32_e32 v158, v158, v158
	v_max_f32_e32 v159, v159, v159
	v_max_f32_e32 v162, v162, v162
	v_max_f32_e32 v163, v163, v163
	v_max_f32_e32 v154, 0x358637bd, v154
	v_max_f32_e32 v155, 0x358637bd, v155
	v_max_f32_e32 v156, 0x358637bd, v156
	v_max_f32_e32 v157, 0x358637bd, v157
	v_max_f32_e32 v158, 0x358637bd, v158
	v_max_f32_e32 v159, 0x358637bd, v159
	v_max_f32_e32 v162, 0x358637bd, v162
	v_max_f32_e32 v163, 0x358637bd, v163
	v_pk_mul_f32 v[80:81], v[80:81], v[154:155]
	v_pk_mul_f32 v[82:83], v[82:83], v[156:157]
	v_pk_mul_f32 v[76:77], v[76:77], v[158:159]
	v_pk_mul_f32 v[78:79], v[78:79], v[162:163]
	v_cvt_pk_bf16_f32 v80, v80, v81
	v_cvt_pk_bf16_f32 v81, v82, v83
	v_cvt_pk_bf16_f32 v82, v76, v77
	v_cvt_pk_bf16_f32 v83, v78, v79
	global_store_dwordx4 v148, v[80:83], s[100:101] offset:256
	s_waitcnt vmcnt(15)
	v_lshlrev_b32_e32 v154, 16, v214
	v_and_b32_e32 v155, 0xffff0000, v214
	v_lshlrev_b32_e32 v156, 16, v215
	v_and_b32_e32 v157, 0xffff0000, v215
	v_lshlrev_b32_e32 v158, 16, v216
	v_and_b32_e32 v159, 0xffff0000, v216
	v_lshlrev_b32_e32 v162, 16, v217
	v_and_b32_e32 v163, 0xffff0000, v217
	v_max_f32_e32 v154, v154, v154
	v_max_f32_e32 v155, v155, v155
	v_max_f32_e32 v156, v156, v156
	v_max_f32_e32 v157, v157, v157
	v_max_f32_e32 v158, v158, v158
	v_max_f32_e32 v159, v159, v159
	v_max_f32_e32 v162, v162, v162
	v_max_f32_e32 v163, v163, v163
	v_max_f32_e32 v154, 0x358637bd, v154
	v_max_f32_e32 v155, 0x358637bd, v155
	v_max_f32_e32 v156, 0x358637bd, v156
	v_max_f32_e32 v157, 0x358637bd, v157
	v_max_f32_e32 v158, 0x358637bd, v158
	v_max_f32_e32 v159, 0x358637bd, v159
	v_max_f32_e32 v162, 0x358637bd, v162
	v_max_f32_e32 v163, 0x358637bd, v163
	v_pk_mul_f32 v[104:105], v[104:105], v[154:155]
	v_pk_mul_f32 v[106:107], v[106:107], v[156:157]
	v_pk_mul_f32 v[100:101], v[100:101], v[158:159]
	v_pk_mul_f32 v[102:103], v[102:103], v[162:163]
	v_cvt_pk_bf16_f32 v104, v104, v105
	v_cvt_pk_bf16_f32 v105, v106, v107
	v_cvt_pk_bf16_f32 v106, v100, v101
	v_cvt_pk_bf16_f32 v107, v102, v103
	s_add_u32 s100, s50, 0x18000
	s_addc_u32 s101, s51, 0
	global_store_dwordx4 v148, v[104:107], s[100:101]
	s_waitcnt vmcnt(15)
	v_lshlrev_b32_e32 v154, 16, v218
	v_and_b32_e32 v155, 0xffff0000, v218
	v_lshlrev_b32_e32 v156, 16, v219
	v_and_b32_e32 v157, 0xffff0000, v219
	v_lshlrev_b32_e32 v158, 16, v220
	v_and_b32_e32 v159, 0xffff0000, v220
	v_lshlrev_b32_e32 v162, 16, v221
	v_and_b32_e32 v163, 0xffff0000, v221
	v_max_f32_e32 v154, v154, v154
	v_max_f32_e32 v155, v155, v155
	v_max_f32_e32 v156, v156, v156
	v_max_f32_e32 v157, v157, v157
	v_max_f32_e32 v158, v158, v158
	v_max_f32_e32 v159, v159, v159
	v_max_f32_e32 v162, v162, v162
	v_max_f32_e32 v163, v163, v163
	v_max_f32_e32 v154, 0x358637bd, v154
	v_max_f32_e32 v155, 0x358637bd, v155
	v_max_f32_e32 v156, 0x358637bd, v156
	v_max_f32_e32 v157, 0x358637bd, v157
	v_max_f32_e32 v158, 0x358637bd, v158
	v_max_f32_e32 v159, 0x358637bd, v159
	v_max_f32_e32 v162, 0x358637bd, v162
	v_max_f32_e32 v163, 0x358637bd, v163
	v_pk_mul_f32 v[72:73], v[72:73], v[154:155]
	v_pk_mul_f32 v[74:75], v[74:75], v[156:157]
	v_pk_mul_f32 v[68:69], v[68:69], v[158:159]
	v_pk_mul_f32 v[70:71], v[70:71], v[162:163]
	v_cvt_pk_bf16_f32 v72, v72, v73
	v_cvt_pk_bf16_f32 v73, v74, v75
	v_cvt_pk_bf16_f32 v74, v68, v69
	v_cvt_pk_bf16_f32 v75, v70, v71
	global_store_dwordx4 v148, v[72:75], s[100:101] offset:256
	s_waitcnt vmcnt(15)
	v_lshlrev_b32_e32 v154, 16, v222
	v_and_b32_e32 v155, 0xffff0000, v222
	v_lshlrev_b32_e32 v156, 16, v223
	v_and_b32_e32 v157, 0xffff0000, v223
	v_lshlrev_b32_e32 v158, 16, v224
	v_and_b32_e32 v159, 0xffff0000, v224
	v_lshlrev_b32_e32 v162, 16, v225
	v_and_b32_e32 v163, 0xffff0000, v225
	v_max_f32_e32 v154, v154, v154
	v_max_f32_e32 v155, v155, v155
	v_max_f32_e32 v156, v156, v156
	v_max_f32_e32 v157, v157, v157
	v_max_f32_e32 v158, v158, v158
	v_max_f32_e32 v159, v159, v159
	v_max_f32_e32 v162, v162, v162
	v_max_f32_e32 v163, v163, v163
	v_max_f32_e32 v154, 0x358637bd, v154
	v_max_f32_e32 v155, 0x358637bd, v155
	v_max_f32_e32 v156, 0x358637bd, v156
	v_max_f32_e32 v157, 0x358637bd, v157
	v_max_f32_e32 v158, 0x358637bd, v158
	v_max_f32_e32 v159, 0x358637bd, v159
	v_max_f32_e32 v162, 0x358637bd, v162
	v_max_f32_e32 v163, 0x358637bd, v163
	v_pk_mul_f32 v[64:65], v[64:65], v[154:155]
	v_pk_mul_f32 v[66:67], v[66:67], v[156:157]
	v_pk_mul_f32 v[60:61], v[60:61], v[158:159]
	v_pk_mul_f32 v[62:63], v[62:63], v[162:163]
	v_cvt_pk_bf16_f32 v64, v64, v65
	v_cvt_pk_bf16_f32 v65, v66, v67
	v_cvt_pk_bf16_f32 v66, v60, v61
	v_cvt_pk_bf16_f32 v67, v62, v63
	s_add_u32 s100, s50, 0x40000
	s_addc_u32 s101, s51, 0
	global_store_dwordx4 v148, v[64:67], s[100:101]
	s_waitcnt vmcnt(15)
; __device__ __forceinline__ unsigned pk2(float lo, float hi) { const f32x2_t v = {lo, hi}; const bf16v2_t b = __builtin_convertvector(v, bf16v2_t); return __builtin_bit_cast(unsigned, b); }
;     __device__ __forceinline__ void operator()(AccT& acc, const pg8::Unit& u, int wr, int wc, int fr_, int fq_) const {
;     ...
;                         const f32x4 t0 = b0 * acc[ai][bj][m][0], t1 = b1 * acc[ai][bj][m][1];
;                         u32x4 w; w[0] = pk2(t0[0], t0[1]); w[1] = pk2(t0[2], t0[3]); w[2] = pk2(t1[0], t1[1]); w[3] = pk2(t1[2], t1[3]);
;                         *(u32x4*)(MB + o) = w;
	v_lshlrev_b32_e32 v154, 16, v226
	v_and_b32_e32 v155, 0xffff0000, v226
	v_lshlrev_b32_e32 v156, 16, v227
	v_and_b32_e32 v157, 0xffff0000, v227
	v_lshlrev_b32_e32 v158, 16, v228
	v_and_b32_e32 v159, 0xffff0000, v228
	v_lshlrev_b32_e32 v162, 16, v229
	v_and_b32_e32 v163, 0xffff0000, v229
	v_max_f32_e32 v154, v154, v154
	v_max_f32_e32 v155, v155, v155
	v_max_f32_e32 v156, v156, v156
	v_max_f32_e32 v157, v157, v157
	v_max_f32_e32 v158, v158, v158
	v_max_f32_e32 v159, v159, v159
	v_max_f32_e32 v162, v162, v162
	v_max_f32_e32 v163, v163, v163
	v_max_f32_e32 v154, 0x358637bd, v154
	v_max_f32_e32 v155, 0x358637bd, v155
	v_max_f32_e32 v156, 0x358637bd, v156
	v_max_f32_e32 v157, 0x358637bd, v157
	v_max_f32_e32 v158, 0x358637bd, v158
	v_max_f32_e32 v159, 0x358637bd, v159
	v_max_f32_e32 v162, 0x358637bd, v162
	v_max_f32_e32 v163, 0x358637bd, v163
	v_pk_mul_f32 v[32:33], v[32:33], v[154:155]
	v_pk_mul_f32 v[34:35], v[34:35], v[156:157]
	v_pk_mul_f32 v[28:29], v[28:29], v[158:159]
	v_pk_mul_f32 v[30:31], v[30:31], v[162:163]
	v_cvt_pk_bf16_f32 v32, v32, v33
	v_cvt_pk_bf16_f32 v33, v34, v35
	v_cvt_pk_bf16_f32 v34, v28, v29
	v_cvt_pk_bf16_f32 v35, v30, v31
	global_store_dwordx4 v148, v[32:35], s[100:101] offset:256
	s_waitcnt vmcnt(15)
	v_lshlrev_b32_e32 v154, 16, v230
	v_and_b32_e32 v155, 0xffff0000, v230
	v_lshlrev_b32_e32 v156, 16, v231
	v_and_b32_e32 v157, 0xffff0000, v231
	v_lshlrev_b32_e32 v158, 16, v232
	v_and_b32_e32 v159, 0xffff0000, v232
	v_lshlrev_b32_e32 v162, 16, v233
	v_and_b32_e32 v163, 0xffff0000, v233
	v_max_f32_e32 v154, v154, v154
	v_max_f32_e32 v155, v155, v155
	v_max_f32_e32 v156, v156, v156
	v_max_f32_e32 v157, v157, v157
	v_max_f32_e32 v158, v158, v158
	v_max_f32_e32 v159, v159, v159
	v_max_f32_e32 v162, v162, v162
	v_max_f32_e32 v163, v163, v163
	v_max_f32_e32 v154, 0x358637bd, v154
	v_max_f32_e32 v155, 0x358637bd, v155
	v_max_f32_e32 v156, 0x358637bd, v156
	v_max_f32_e32 v157, 0x358637bd, v157
	v_max_f32_e32 v158, 0x358637bd, v158
	v_max_f32_e32 v159, 0x358637bd, v159
	v_max_f32_e32 v162, 0x358637bd, v162
	v_max_f32_e32 v163, 0x358637bd, v163
	v_pk_mul_f32 v[56:57], v[56:57], v[154:155]
	v_pk_mul_f32 v[58:59], v[58:59], v[156:157]
	v_pk_mul_f32 v[52:53], v[52:53], v[158:159]
	v_pk_mul_f32 v[54:55], v[54:55], v[162:163]
	v_cvt_pk_bf16_f32 v56, v56, v57
	v_cvt_pk_bf16_f32 v57, v58, v59
	v_cvt_pk_bf16_f32 v58, v52, v53
	v_cvt_pk_bf16_f32 v59, v54, v55
	s_add_u32 s100, s50, 0x48000
	s_addc_u32 s101, s51, 0
	global_store_dwordx4 v148, v[56:59], s[100:101]
	s_waitcnt vmcnt(15)
	v_lshlrev_b32_e32 v154, 16, v234
	v_and_b32_e32 v155, 0xffff0000, v234
	v_lshlrev_b32_e32 v156, 16, v235
	v_and_b32_e32 v157, 0xffff0000, v235
	v_lshlrev_b32_e32 v158, 16, v236
	v_and_b32_e32 v159, 0xffff0000, v236
	v_lshlrev_b32_e32 v162, 16, v237
	v_and_b32_e32 v163, 0xffff0000, v237
	v_max_f32_e32 v154, v154, v154
	v_max_f32_e32 v155, v155, v155
	v_max_f32_e32 v156, v156, v156
	v_max_f32_e32 v157, v157, v157
	v_max_f32_e32 v158, v158, v158
	v_max_f32_e32 v159, v159, v159
	v_max_f32_e32 v162, v162, v162
	v_max_f32_e32 v163, v163, v163
	v_max_f32_e32 v154, 0x358637bd, v154
	v_max_f32_e32 v155, 0x358637bd, v155
	v_max_f32_e32 v156, 0x358637bd, v156
	v_max_f32_e32 v157, 0x358637bd, v157
	v_max_f32_e32 v158, 0x358637bd, v158
	v_max_f32_e32 v159, 0x358637bd, v159
	v_max_f32_e32 v162, 0x358637bd, v162
	v_max_f32_e32 v163, 0x358637bd, v163
	v_pk_mul_f32 v[24:25], v[24:25], v[154:155]
	v_pk_mul_f32 v[26:27], v[26:27], v[156:157]
	v_pk_mul_f32 v[20:21], v[20:21], v[158:159]
	v_pk_mul_f32 v[22:23], v[22:23], v[162:163]
	v_cvt_pk_bf16_f32 v24, v24, v25
	v_cvt_pk_bf16_f32 v25, v26, v27
	v_cvt_pk_bf16_f32 v26, v20, v21
	v_cvt_pk_bf16_f32 v27, v22, v23
	global_store_dwordx4 v148, v[24:27], s[100:101] offset:256
	s_waitcnt vmcnt(15)
	v_lshlrev_b32_e32 v154, 16, v238
	v_and_b32_e32 v155, 0xffff0000, v238
	v_lshlrev_b32_e32 v156, 16, v239
	v_and_b32_e32 v157, 0xffff0000, v239
	v_lshlrev_b32_e32 v158, 16, v240
	v_and_b32_e32 v159, 0xffff0000, v240
	v_lshlrev_b32_e32 v162, 16, v241
	v_and_b32_e32 v163, 0xffff0000, v241
	v_max_f32_e32 v154, v154, v154
	v_max_f32_e32 v155, v155, v155
	v_max_f32_e32 v156, v156, v156
	v_max_f32_e32 v157, v157, v157
	v_max_f32_e32 v158, v158, v158
	v_max_f32_e32 v159, v159, v159
	v_max_f32_e32 v162, v162, v162
	v_max_f32_e32 v163, v163, v163
	v_max_f32_e32 v154, 0x358637bd, v154
	v_max_f32_e32 v155, 0x358637bd, v155
	v_max_f32_e32 v156, 0x358637bd, v156
	v_max_f32_e32 v157, 0x358637bd, v157
	v_max_f32_e32 v158, 0x358637bd, v158
	v_max_f32_e32 v159, 0x358637bd, v159
	v_max_f32_e32 v162, 0x358637bd, v162
	v_max_f32_e32 v163, 0x358637bd, v163
	v_pk_mul_f32 v[48:49], v[48:49], v[154:155]
	v_pk_mul_f32 v[50:51], v[50:51], v[156:157]
	v_pk_mul_f32 v[44:45], v[44:45], v[158:159]
	v_pk_mul_f32 v[46:47], v[46:47], v[162:163]
	v_cvt_pk_bf16_f32 v48, v48, v49
	v_cvt_pk_bf16_f32 v49, v50, v51
	v_cvt_pk_bf16_f32 v50, v44, v45
	v_cvt_pk_bf16_f32 v51, v46, v47
	s_add_u32 s100, s50, 0x50000
	s_addc_u32 s101, s51, 0
	global_store_dwordx4 v148, v[48:51], s[100:101]
	s_waitcnt vmcnt(15)
; __device__ __forceinline__ unsigned pk2(float lo, float hi) { const f32x2_t v = {lo, hi}; const bf16v2_t b = __builtin_convertvector(v, bf16v2_t); return __builtin_bit_cast(unsigned, b); }
; __device__ __forceinline__ float bflo(unsigned u) { return __uint_as_float(u << 16); }
; __device__ __forceinline__ float bfhi(unsigned u) { return __uint_as_float(u & 0xffff0000u); }
;     __device__ __forceinline__ void operator()(AccT& acc, const pg8::Unit& u, int wr, int wc, int fr_, int fq_) const {
;     ...
;         if (u.sub & 2) {
;             const bf16_t* G = (u.sub & 1) ? GB : GA;
;             bf16_t* P = (bf16_t*)(ws + WS_PART2) + (size_t)u.sp * (2048 * D);
; #pragma unroll
;             for (int ai = 0; ai < 2; ++ai)
; #pragma unroll
;                 for (int m = 0; m < 4; ++m) {
;                     const size_t ro = (size_t)(row0 + ai * 128 + m * 16) * D + col0;
;                     const size_t po = (size_t)(row0 - 16384 + ai * 128 + m * 16) * D + col0;
; #pragma unroll
;                     for (int bj = 0; bj < 2; ++bj) {
;                         const u32x4 gv = *(const u32x4*)(G + ro + bj * 128);
;                         f32x4 s0, s1; s0[0] = bflo(gv[0]); s0[1] = bfhi(gv[0]); s0[2] = bflo(gv[1]); s0[3] = bfhi(gv[1]); s1[0] = bflo(gv[2]); s1[1] = bfhi(gv[2]); s1[2] = bflo(gv[3]); s1[3] = bfhi(gv[3]);
;                         const f32x4 t0 = s0 * acc[ai][bj][m][0], t1 = s1 * acc[ai][bj][m][1];
;                         u32x4 o; o[0] = pk2(t0[0], t0[1]); o[1] = pk2(t0[2], t0[3]); o[2] = pk2(t1[0], t1[1]); o[3] = pk2(t1[2], t1[3]);
;                         *(u32x4*)(P + po + bj * 128) = o;
;     ...
;                         const f32x4 t0 = b0 * acc[ai][bj][m][0], t1 = b1 * acc[ai][bj][m][1];
;                         u32x4 w; w[0] = pk2(t0[0], t0[1]); w[1] = pk2(t0[2], t0[3]); w[2] = pk2(t1[0], t1[1]); w[3] = pk2(t1[2], t1[3]);
;                         *(u32x4*)(MB + o) = w;
	v_lshlrev_b32_e32 v154, 16, v242
	v_and_b32_e32 v155, 0xffff0000, v242
	v_lshlrev_b32_e32 v156, 16, v243
	v_and_b32_e32 v157, 0xffff0000, v243
	v_lshlrev_b32_e32 v158, 16, v244
	v_and_b32_e32 v159, 0xffff0000, v244
	v_lshlrev_b32_e32 v162, 16, v245
	v_and_b32_e32 v163, 0xffff0000, v245
	v_max_f32_e32 v154, v154, v154
	v_max_f32_e32 v155, v155, v155
	v_max_f32_e32 v156, v156, v156
	v_max_f32_e32 v157, v157, v157
	v_max_f32_e32 v158, v158, v158
	v_max_f32_e32 v159, v159, v159
	v_max_f32_e32 v162, v162, v162
	v_max_f32_e32 v163, v163, v163
	v_max_f32_e32 v154, 0x358637bd, v154
	v_max_f32_e32 v155, 0x358637bd, v155
	v_max_f32_e32 v156, 0x358637bd, v156
	v_max_f32_e32 v157, 0x358637bd, v157
	v_max_f32_e32 v158, 0x358637bd, v158
	v_max_f32_e32 v159, 0x358637bd, v159
	v_max_f32_e32 v162, 0x358637bd, v162
	v_max_f32_e32 v163, 0x358637bd, v163
	v_pk_mul_f32 v[16:17], v[16:17], v[154:155]
	v_pk_mul_f32 v[18:19], v[18:19], v[156:157]
	v_pk_mul_f32 v[12:13], v[12:13], v[158:159]
	v_pk_mul_f32 v[14:15], v[14:15], v[162:163]
	v_cvt_pk_bf16_f32 v16, v16, v17
	v_cvt_pk_bf16_f32 v17, v18, v19
	v_cvt_pk_bf16_f32 v18, v12, v13
	v_cvt_pk_bf16_f32 v19, v14, v15
	global_store_dwordx4 v148, v[16:19], s[100:101] offset:256
	s_waitcnt vmcnt(15)
	v_lshlrev_b32_e32 v154, 16, v246
	v_and_b32_e32 v155, 0xffff0000, v246
	v_lshlrev_b32_e32 v156, 16, v247
	v_and_b32_e32 v157, 0xffff0000, v247
	v_lshlrev_b32_e32 v158, 16, v248
	v_and_b32_e32 v159, 0xffff0000, v248
	v_lshlrev_b32_e32 v162, 16, v249
	v_and_b32_e32 v163, 0xffff0000, v249
	v_max_f32_e32 v154, v154, v154
	v_max_f32_e32 v155, v155, v155
	v_max_f32_e32 v156, v156, v156
	v_max_f32_e32 v157, v157, v157
	v_max_f32_e32 v158, v158, v158
	v_max_f32_e32 v159, v159, v159
	v_max_f32_e32 v162, v162, v162
	v_max_f32_e32 v163, v163, v163
	v_max_f32_e32 v154, 0x358637bd, v154
	v_max_f32_e32 v155, 0x358637bd, v155
	v_max_f32_e32 v156, 0x358637bd, v156
	v_max_f32_e32 v157, 0x358637bd, v157
	v_max_f32_e32 v158, 0x358637bd, v158
	v_max_f32_e32 v159, 0x358637bd, v159
	v_max_f32_e32 v162, 0x358637bd, v162
	v_max_f32_e32 v163, 0x358637bd, v163
	v_pk_mul_f32 v[40:41], v[40:41], v[154:155]
	v_pk_mul_f32 v[42:43], v[42:43], v[156:157]
	v_pk_mul_f32 v[36:37], v[36:37], v[158:159]
	v_pk_mul_f32 v[38:39], v[38:39], v[162:163]
	v_cvt_pk_bf16_f32 v40, v40, v41
	v_cvt_pk_bf16_f32 v41, v42, v43
	v_cvt_pk_bf16_f32 v42, v36, v37
	v_cvt_pk_bf16_f32 v43, v38, v39
	s_add_u32 s100, s50, 0x58000
	s_addc_u32 s101, s51, 0
	global_store_dwordx4 v148, v[40:43], s[100:101]
	s_waitcnt vmcnt(15)
	v_lshlrev_b32_e32 v154, 16, v250
	v_and_b32_e32 v155, 0xffff0000, v250
	v_lshlrev_b32_e32 v156, 16, v251
	v_and_b32_e32 v157, 0xffff0000, v251
	v_lshlrev_b32_e32 v158, 16, v252
	v_and_b32_e32 v159, 0xffff0000, v252
	v_lshlrev_b32_e32 v162, 16, v253
	v_and_b32_e32 v163, 0xffff0000, v253
	v_max_f32_e32 v154, v154, v154
	v_max_f32_e32 v155, v155, v155
	v_max_f32_e32 v156, v156, v156
	v_max_f32_e32 v157, v157, v157
	v_max_f32_e32 v158, v158, v158
	v_max_f32_e32 v159, v159, v159
	v_max_f32_e32 v162, v162, v162
	v_max_f32_e32 v163, v163, v163
	v_max_f32_e32 v154, 0x358637bd, v154
	v_max_f32_e32 v155, 0x358637bd, v155
	v_max_f32_e32 v156, 0x358637bd, v156
	v_max_f32_e32 v157, 0x358637bd, v157
	v_max_f32_e32 v158, 0x358637bd, v158
	v_max_f32_e32 v159, 0x358637bd, v159
	v_max_f32_e32 v162, 0x358637bd, v162
	v_max_f32_e32 v163, 0x358637bd, v163
	v_pk_mul_f32 v[8:9], v[8:9], v[154:155]
	v_pk_mul_f32 v[10:11], v[10:11], v[156:157]
	v_pk_mul_f32 v[4:5], v[4:5], v[158:159]
	v_pk_mul_f32 v[6:7], v[6:7], v[162:163]
	v_cvt_pk_bf16_f32 v8, v8, v9
	v_cvt_pk_bf16_f32 v9, v10, v11
	v_cvt_pk_bf16_f32 v10, v4, v5
	v_cvt_pk_bf16_f32 v11, v6, v7
	global_store_dwordx4 v148, v[8:11], s[100:101] offset:256
	s_branch .LBB0_543
.Lmg_tail:
	s_bitcmp0_b32 s39, 0
	s_cselect_b32 s5, s55, s57
	s_cselect_b32 s4, s54, s56
	s_lshl_b32 s10, s14, 22
	s_add_u32 s10, s48, s10
	s_addc_u32 s11, s49, 0
	s_sub_u32 s10, s10, 0x2000000
	s_subb_u32 s11, s11, 0
	s_mov_b32 s98, s4
	s_mov_b32 s99, s5
	global_load_dwordx4 v[190:193], v148, s[98:99]
	global_load_dwordx4 v[194:197], v148, s[98:99] offset:256
	s_add_u32 s98, s4, 0x8000
	s_addc_u32 s99, s5, 0
	global_load_dwordx4 v[198:201], v148, s[98:99]
	global_load_dwordx4 v[202:205], v148, s[98:99] offset:256
	s_add_u32 s98, s4, 0x10000
	s_addc_u32 s99, s5, 0
	global_load_dwordx4 v[206:209], v148, s[98:99]
	global_load_dwordx4 v[210:213], v148, s[98:99] offset:256
	s_add_u32 s98, s4, 0x18000
	s_addc_u32 s99, s5, 0
	global_load_dwordx4 v[214:217], v148, s[98:99]
	global_load_dwordx4 v[218:221], v148, s[98:99] offset:256
	s_add_u32 s98, s4, 0x40000
	s_addc_u32 s99, s5, 0
	global_load_dwordx4 v[222:225], v148, s[98:99]
	global_load_dwordx4 v[226:229], v148, s[98:99] offset:256
	s_add_u32 s98, s4, 0x48000
	s_addc_u32 s99, s5, 0
	global_load_dwordx4 v[230:233], v148, s[98:99]
	global_load_dwordx4 v[234:237], v148, s[98:99] offset:256
	s_add_u32 s98, s4, 0x50000
	s_addc_u32 s99, s5, 0
	global_load_dwordx4 v[238:241], v148, s[98:99]
	global_load_dwordx4 v[242:245], v148, s[98:99] offset:256
	s_add_u32 s98, s4, 0x58000
	s_addc_u32 s99, s5, 0
	global_load_dwordx4 v[246:249], v148, s[98:99]
	global_load_dwordx4 v[250:253], v148, s[98:99] offset:256
	s_waitcnt vmcnt(15)
	v_lshlrev_b32_e32 v154, 16, v190
	v_and_b32_e32 v155, 0xffff0000, v190
	v_lshlrev_b32_e32 v156, 16, v191
	v_and_b32_e32 v157, 0xffff0000, v191
	v_lshlrev_b32_e32 v158, 16, v192
	v_and_b32_e32 v159, 0xffff0000, v192
	v_lshlrev_b32_e32 v162, 16, v193
	v_and_b32_e32 v163, 0xffff0000, v193
	v_pk_mul_f32 v[128:129], v[128:129], v[154:155]
	v_pk_mul_f32 v[130:131], v[130:131], v[156:157]
	v_pk_mul_f32 v[124:125], v[124:125], v[158:159]
	v_pk_mul_f32 v[126:127], v[126:127], v[162:163]
	v_cvt_pk_bf16_f32 v128, v128, v129
	v_cvt_pk_bf16_f32 v129, v130, v131
	v_cvt_pk_bf16_f32 v130, v124, v125
	v_cvt_pk_bf16_f32 v131, v126, v127
	s_mov_b32 s100, s10
	s_mov_b32 s101, s11
	global_store_dwordx4 v148, v[128:131], s[100:101]
	s_waitcnt vmcnt(15)
; __device__ __forceinline__ unsigned pk2(float lo, float hi) { const f32x2_t v = {lo, hi}; const bf16v2_t b = __builtin_convertvector(v, bf16v2_t); return __builtin_bit_cast(unsigned, b); }
; __device__ __forceinline__ float bflo(unsigned u) { return __uint_as_float(u << 16); }
; __device__ __forceinline__ float bfhi(unsigned u) { return __uint_as_float(u & 0xffff0000u); }
;     __device__ __forceinline__ void operator()(AccT& acc, const pg8::Unit& u, int wr, int wc, int fr_, int fq_) const {
;     ...
;                     const size_t ro = (size_t)(row0 + ai * 128 + m * 16) * D + col0;
;                     const size_t po = (size_t)(row0 - 16384 + ai * 128 + m * 16) * D + col0;
; #pragma unroll
;                     for (int bj = 0; bj < 2; ++bj) {
;                         const u32x4 gv = *(const u32x4*)(G + ro + bj * 128);
;                         f32x4 s0, s1; s0[0] = bflo(gv[0]); s0[1] = bfhi(gv[0]); s0[2] = bflo(gv[1]); s0[3] = bfhi(gv[1]); s1[0] = bflo(gv[2]); s1[1] = bfhi(gv[2]); s1[2] = bflo(gv[3]); s1[3] = bfhi(gv[3]);
;                         const f32x4 t0 = s0 * acc[ai][bj][m][0], t1 = s1 * acc[ai][bj][m][1];
;                         u32x4 o; o[0] = pk2(t0[0], t0[1]); o[1] = pk2(t0[2], t0[3]); o[2] = pk2(t1[0], t1[1]); o[3] = pk2(t1[2], t1[3]);
;                         *(u32x4*)(P + po + bj * 128) = o;
	v_lshlrev_b32_e32 v154, 16, v194
	v_and_b32_e32 v155, 0xffff0000, v194
	v_lshlrev_b32_e32 v156, 16, v195
	v_and_b32_e32 v157, 0xffff0000, v195
	v_lshlrev_b32_e32 v158, 16, v196
	v_and_b32_e32 v159, 0xffff0000, v196
	v_lshlrev_b32_e32 v162, 16, v197
	v_and_b32_e32 v163, 0xffff0000, v197
	v_pk_mul_f32 v[96:97], v[96:97], v[154:155]
	v_pk_mul_f32 v[98:99], v[98:99], v[156:157]
	v_pk_mul_f32 v[92:93], v[92:93], v[158:159]
	v_pk_mul_f32 v[94:95], v[94:95], v[162:163]
	v_cvt_pk_bf16_f32 v96, v96, v97
	v_cvt_pk_bf16_f32 v97, v98, v99
	v_cvt_pk_bf16_f32 v98, v92, v93
	v_cvt_pk_bf16_f32 v99, v94, v95
	global_store_dwordx4 v148, v[96:99], s[100:101] offset:256
	s_waitcnt vmcnt(15)
	v_lshlrev_b32_e32 v154, 16, v198
	v_and_b32_e32 v155, 0xffff0000, v198
	v_lshlrev_b32_e32 v156, 16, v199
	v_and_b32_e32 v157, 0xffff0000, v199
	v_lshlrev_b32_e32 v158, 16, v200
	v_and_b32_e32 v159, 0xffff0000, v200
	v_lshlrev_b32_e32 v162, 16, v201
	v_and_b32_e32 v163, 0xffff0000, v201
	v_pk_mul_f32 v[120:121], v[120:121], v[154:155]
	v_pk_mul_f32 v[122:123], v[122:123], v[156:157]
	v_pk_mul_f32 v[116:117], v[116:117], v[158:159]
	v_pk_mul_f32 v[118:119], v[118:119], v[162:163]
	v_cvt_pk_bf16_f32 v120, v120, v121
	v_cvt_pk_bf16_f32 v121, v122, v123
	v_cvt_pk_bf16_f32 v122, v116, v117
	v_cvt_pk_bf16_f32 v123, v118, v119
	s_add_u32 s100, s10, 0x8000
	s_addc_u32 s101, s11, 0
	global_store_dwordx4 v148, v[120:123], s[100:101]
	s_waitcnt vmcnt(15)
	v_lshlrev_b32_e32 v154, 16, v202
	v_and_b32_e32 v155, 0xffff0000, v202
	v_lshlrev_b32_e32 v156, 16, v203
	v_and_b32_e32 v157, 0xffff0000, v203
	v_lshlrev_b32_e32 v158, 16, v204
	v_and_b32_e32 v159, 0xffff0000, v204
	v_lshlrev_b32_e32 v162, 16, v205
	v_and_b32_e32 v163, 0xffff0000, v205
	v_pk_mul_f32 v[88:89], v[88:89], v[154:155]
	v_pk_mul_f32 v[90:91], v[90:91], v[156:157]
	v_pk_mul_f32 v[84:85], v[84:85], v[158:159]
	v_pk_mul_f32 v[86:87], v[86:87], v[162:163]
	v_cvt_pk_bf16_f32 v88, v88, v89
	v_cvt_pk_bf16_f32 v89, v90, v91
	v_cvt_pk_bf16_f32 v90, v84, v85
	v_cvt_pk_bf16_f32 v91, v86, v87
	global_store_dwordx4 v148, v[88:91], s[100:101] offset:256
	s_waitcnt vmcnt(15)
	v_lshlrev_b32_e32 v154, 16, v206
	v_and_b32_e32 v155, 0xffff0000, v206
	v_lshlrev_b32_e32 v156, 16, v207
	v_and_b32_e32 v157, 0xffff0000, v207
	v_lshlrev_b32_e32 v158, 16, v208
	v_and_b32_e32 v159, 0xffff0000, v208
	v_lshlrev_b32_e32 v162, 16, v209
	v_and_b32_e32 v163, 0xffff0000, v209
	v_pk_mul_f32 v[112:113], v[112:113], v[154:155]
	v_pk_mul_f32 v[114:115], v[114:115], v[156:157]
	v_pk_mul_f32 v[108:109], v[108:109], v[158:159]
	v_pk_mul_f32 v[110:111], v[110:111], v[162:163]
	v_cvt_pk_bf16_f32 v112, v112, v113
	v_cvt_pk_bf16_f32 v113, v114, v115
	v_cvt_pk_bf16_f32 v114, v108, v109
	v_cvt_pk_bf16_f32 v115, v110, v111
	s_add_u32 s100, s10, 0x10000
	s_addc_u32 s101, s11, 0
	global_store_dwordx4 v148, v[112:115], s[100:101]
	s_waitcnt vmcnt(15)
	v_lshlrev_b32_e32 v154, 16, v210
	v_and_b32_e32 v155, 0xffff0000, v210
	v_lshlrev_b32_e32 v156, 16, v211
	v_and_b32_e32 v157, 0xffff0000, v211
	v_lshlrev_b32_e32 v158, 16, v212
	v_and_b32_e32 v159, 0xffff0000, v212
	v_lshlrev_b32_e32 v162, 16, v213
	v_and_b32_e32 v163, 0xffff0000, v213
	v_pk_mul_f32 v[80:81], v[80:81], v[154:155]
	v_pk_mul_f32 v[82:83], v[82:83], v[156:157]
	v_pk_mul_f32 v[76:77], v[76:77], v[158:159]
	v_pk_mul_f32 v[78:79], v[78:79], v[162:163]
	v_cvt_pk_bf16_f32 v80, v80, v81
	v_cvt_pk_bf16_f32 v81, v82, v83
	v_cvt_pk_bf16_f32 v82, v76, v77
	v_cvt_pk_bf16_f32 v83, v78, v79
	global_store_dwordx4 v148, v[80:83], s[100:101] offset:256
	s_waitcnt vmcnt(15)
	v_lshlrev_b32_e32 v154, 16, v214
	v_and_b32_e32 v155, 0xffff0000, v214
	v_lshlrev_b32_e32 v156, 16, v215
	v_and_b32_e32 v157, 0xffff0000, v215
	v_lshlrev_b32_e32 v158, 16, v216
	v_and_b32_e32 v159, 0xffff0000, v216
	v_lshlrev_b32_e32 v162, 16, v217
	v_and_b32_e32 v163, 0xffff0000, v217
	v_pk_mul_f32 v[104:105], v[104:105], v[154:155]
	v_pk_mul_f32 v[106:107], v[106:107], v[156:157]
	v_pk_mul_f32 v[100:101], v[100:101], v[158:159]
	v_pk_mul_f32 v[102:103], v[102:103], v[162:163]
	v_cvt_pk_bf16_f32 v104, v104, v105
	v_cvt_pk_bf16_f32 v105, v106, v107
	v_cvt_pk_bf16_f32 v106, v100, v101
	v_cvt_pk_bf16_f32 v107, v102, v103
	s_add_u32 s100, s10, 0x18000
	s_addc_u32 s101, s11, 0
	global_store_dwordx4 v148, v[104:107], s[100:101]
	s_waitcnt vmcnt(15)
	v_lshlrev_b32_e32 v154, 16, v218
	v_and_b32_e32 v155, 0xffff0000, v218
	v_lshlrev_b32_e32 v156, 16, v219
	v_and_b32_e32 v157, 0xffff0000, v219
	v_lshlrev_b32_e32 v158, 16, v220
	v_and_b32_e32 v159, 0xffff0000, v220
	v_lshlrev_b32_e32 v162, 16, v221
	v_and_b32_e32 v163, 0xffff0000, v221
	v_pk_mul_f32 v[72:73], v[72:73], v[154:155]
	v_pk_mul_f32 v[74:75], v[74:75], v[156:157]
	v_pk_mul_f32 v[68:69], v[68:69], v[158:159]
	v_pk_mul_f32 v[70:71], v[70:71], v[162:163]
	v_cvt_pk_bf16_f32 v72, v72, v73
	v_cvt_pk_bf16_f32 v73, v74, v75
	v_cvt_pk_bf16_f32 v74, v68, v69
	v_cvt_pk_bf16_f32 v75, v70, v71
	global_store_dwordx4 v148, v[72:75], s[100:101] offset:256
	s_waitcnt vmcnt(15)
; __device__ __forceinline__ unsigned pk2(float lo, float hi) { const f32x2_t v = {lo, hi}; const bf16v2_t b = __builtin_convertvector(v, bf16v2_t); return __builtin_bit_cast(unsigned, b); }
; __device__ __forceinline__ float bflo(unsigned u) { return __uint_as_float(u << 16); }
; __device__ __forceinline__ float bfhi(unsigned u) { return __uint_as_float(u & 0xffff0000u); }
;     __device__ __forceinline__ void operator()(AccT& acc, const pg8::Unit& u, int wr, int wc, int fr_, int fq_) const {
;     ...
;                     const size_t ro = (size_t)(row0 + ai * 128 + m * 16) * D + col0;
;                     const size_t po = (size_t)(row0 - 16384 + ai * 128 + m * 16) * D + col0;
; #pragma unroll
;                     for (int bj = 0; bj < 2; ++bj) {
;                         const u32x4 gv = *(const u32x4*)(G + ro + bj * 128);
;                         f32x4 s0, s1; s0[0] = bflo(gv[0]); s0[1] = bfhi(gv[0]); s0[2] = bflo(gv[1]); s0[3] = bfhi(gv[1]); s1[0] = bflo(gv[2]); s1[1] = bfhi(gv[2]); s1[2] = bflo(gv[3]); s1[3] = bfhi(gv[3]);
;                         const f32x4 t0 = s0 * acc[ai][bj][m][0], t1 = s1 * acc[ai][bj][m][1];
;                         u32x4 o; o[0] = pk2(t0[0], t0[1]); o[1] = pk2(t0[2], t0[3]); o[2] = pk2(t1[0], t1[1]); o[3] = pk2(t1[2], t1[3]);
;                         *(u32x4*)(P + po + bj * 128) = o;
;                     }
;                 }
	v_lshlrev_b32_e32 v154, 16, v222
	v_and_b32_e32 v155, 0xffff0000, v222
	v_lshlrev_b32_e32 v156, 16, v223
	v_and_b32_e32 v157, 0xffff0000, v223
	v_lshlrev_b32_e32 v158, 16, v224
	v_and_b32_e32 v159, 0xffff0000, v224
	v_lshlrev_b32_e32 v162, 16, v225
	v_and_b32_e32 v163, 0xffff0000, v225
	v_pk_mul_f32 v[64:65], v[64:65], v[154:155]
	v_pk_mul_f32 v[66:67], v[66:67], v[156:157]
	v_pk_mul_f32 v[60:61], v[60:61], v[158:159]
	v_pk_mul_f32 v[62:63], v[62:63], v[162:163]
	v_cvt_pk_bf16_f32 v64, v64, v65
	v_cvt_pk_bf16_f32 v65, v66, v67
	v_cvt_pk_bf16_f32 v66, v60, v61
	v_cvt_pk_bf16_f32 v67, v62, v63
	s_add_u32 s100, s10, 0x40000
	s_addc_u32 s101, s11, 0
	global_store_dwordx4 v148, v[64:67], s[100:101]
	s_waitcnt vmcnt(15)
	v_lshlrev_b32_e32 v154, 16, v226
	v_and_b32_e32 v155, 0xffff0000, v226
	v_lshlrev_b32_e32 v156, 16, v227
	v_and_b32_e32 v157, 0xffff0000, v227
	v_lshlrev_b32_e32 v158, 16, v228
	v_and_b32_e32 v159, 0xffff0000, v228
	v_lshlrev_b32_e32 v162, 16, v229
	v_and_b32_e32 v163, 0xffff0000, v229
	v_pk_mul_f32 v[32:33], v[32:33], v[154:155]
	v_pk_mul_f32 v[34:35], v[34:35], v[156:157]
	v_pk_mul_f32 v[28:29], v[28:29], v[158:159]
	v_pk_mul_f32 v[30:31], v[30:31], v[162:163]
	v_cvt_pk_bf16_f32 v32, v32, v33
	v_cvt_pk_bf16_f32 v33, v34, v35
	v_cvt_pk_bf16_f32 v34, v28, v29
	v_cvt_pk_bf16_f32 v35, v30, v31
	global_store_dwordx4 v148, v[32:35], s[100:101] offset:256
	s_waitcnt vmcnt(15)
	v_lshlrev_b32_e32 v154, 16, v230
	v_and_b32_e32 v155, 0xffff0000, v230
	v_lshlrev_b32_e32 v156, 16, v231
	v_and_b32_e32 v157, 0xffff0000, v231
	v_lshlrev_b32_e32 v158, 16, v232
	v_and_b32_e32 v159, 0xffff0000, v232
	v_lshlrev_b32_e32 v162, 16, v233
	v_and_b32_e32 v163, 0xffff0000, v233
	v_pk_mul_f32 v[56:57], v[56:57], v[154:155]
	v_pk_mul_f32 v[58:59], v[58:59], v[156:157]
	v_pk_mul_f32 v[52:53], v[52:53], v[158:159]
	v_pk_mul_f32 v[54:55], v[54:55], v[162:163]
	v_cvt_pk_bf16_f32 v56, v56, v57
	v_cvt_pk_bf16_f32 v57, v58, v59
	v_cvt_pk_bf16_f32 v58, v52, v53
	v_cvt_pk_bf16_f32 v59, v54, v55
	s_add_u32 s100, s10, 0x48000
	s_addc_u32 s101, s11, 0
	global_store_dwordx4 v148, v[56:59], s[100:101]
	s_waitcnt vmcnt(15)
	v_lshlrev_b32_e32 v154, 16, v234
	v_and_b32_e32 v155, 0xffff0000, v234
	v_lshlrev_b32_e32 v156, 16, v235
	v_and_b32_e32 v157, 0xffff0000, v235
	v_lshlrev_b32_e32 v158, 16, v236
	v_and_b32_e32 v159, 0xffff0000, v236
	v_lshlrev_b32_e32 v162, 16, v237
	v_and_b32_e32 v163, 0xffff0000, v237
	v_pk_mul_f32 v[24:25], v[24:25], v[154:155]
	v_pk_mul_f32 v[26:27], v[26:27], v[156:157]
	v_pk_mul_f32 v[20:21], v[20:21], v[158:159]
	v_pk_mul_f32 v[22:23], v[22:23], v[162:163]
	v_cvt_pk_bf16_f32 v24, v24, v25
	v_cvt_pk_bf16_f32 v25, v26, v27
	v_cvt_pk_bf16_f32 v26, v20, v21
	v_cvt_pk_bf16_f32 v27, v22, v23
	global_store_dwordx4 v148, v[24:27], s[100:101] offset:256
	s_waitcnt vmcnt(15)
	v_lshlrev_b32_e32 v154, 16, v238
	v_and_b32_e32 v155, 0xffff0000, v238
	v_lshlrev_b32_e32 v156, 16, v239
	v_and_b32_e32 v157, 0xffff0000, v239
	v_lshlrev_b32_e32 v158, 16, v240
	v_and_b32_e32 v159, 0xffff0000, v240
	v_lshlrev_b32_e32 v162, 16, v241
	v_and_b32_e32 v163, 0xffff0000, v241
	v_pk_mul_f32 v[48:49], v[48:49], v[154:155]
	v_pk_mul_f32 v[50:51], v[50:51], v[156:157]
	v_pk_mul_f32 v[44:45], v[44:45], v[158:159]
	v_pk_mul_f32 v[46:47], v[46:47], v[162:163]
	v_cvt_pk_bf16_f32 v48, v48, v49
	v_cvt_pk_bf16_f32 v49, v50, v51
	v_cvt_pk_bf16_f32 v50, v44, v45
	v_cvt_pk_bf16_f32 v51, v46, v47
	s_add_u32 s100, s10, 0x50000
	s_addc_u32 s101, s11, 0
	global_store_dwordx4 v148, v[48:51], s[100:101]
	s_waitcnt vmcnt(15)
	v_lshlrev_b32_e32 v154, 16, v242
	v_and_b32_e32 v155, 0xffff0000, v242
	v_lshlrev_b32_e32 v156, 16, v243
	v_and_b32_e32 v157, 0xffff0000, v243
	v_lshlrev_b32_e32 v158, 16, v244
	v_and_b32_e32 v159, 0xffff0000, v244
	v_lshlrev_b32_e32 v162, 16, v245
	v_and_b32_e32 v163, 0xffff0000, v245
	v_pk_mul_f32 v[16:17], v[16:17], v[154:155]
	v_pk_mul_f32 v[18:19], v[18:19], v[156:157]
	v_pk_mul_f32 v[12:13], v[12:13], v[158:159]
	v_pk_mul_f32 v[14:15], v[14:15], v[162:163]
	v_cvt_pk_bf16_f32 v16, v16, v17
	v_cvt_pk_bf16_f32 v17, v18, v19
	v_cvt_pk_bf16_f32 v18, v12, v13
	v_cvt_pk_bf16_f32 v19, v14, v15
	global_store_dwordx4 v148, v[16:19], s[100:101] offset:256
	s_waitcnt vmcnt(15)
	v_lshlrev_b32_e32 v154, 16, v246
	v_and_b32_e32 v155, 0xffff0000, v246
	v_lshlrev_b32_e32 v156, 16, v247
	v_and_b32_e32 v157, 0xffff0000, v247
	v_lshlrev_b32_e32 v158, 16, v248
	v_and_b32_e32 v159, 0xffff0000, v248
	v_lshlrev_b32_e32 v162, 16, v249
	v_and_b32_e32 v163, 0xffff0000, v249
	v_pk_mul_f32 v[40:41], v[40:41], v[154:155]
	v_pk_mul_f32 v[42:43], v[42:43], v[156:157]
	v_pk_mul_f32 v[36:37], v[36:37], v[158:159]
	v_pk_mul_f32 v[38:39], v[38:39], v[162:163]
	v_cvt_pk_bf16_f32 v40, v40, v41
	v_cvt_pk_bf16_f32 v41, v42, v43
	v_cvt_pk_bf16_f32 v42, v36, v37
	v_cvt_pk_bf16_f32 v43, v38, v39
	s_add_u32 s100, s10, 0x58000
	s_addc_u32 s101, s11, 0
	global_store_dwordx4 v148, v[40:43], s[100:101]
	s_waitcnt vmcnt(15)
	v_lshlrev_b32_e32 v154, 16, v250
	v_and_b32_e32 v155, 0xffff0000, v250
	v_lshlrev_b32_e32 v156, 16, v251
	v_and_b32_e32 v157, 0xffff0000, v251
	v_lshlrev_b32_e32 v158, 16, v252
	v_and_b32_e32 v159, 0xffff0000, v252
	v_lshlrev_b32_e32 v162, 16, v253
	v_and_b32_e32 v163, 0xffff0000, v253
	v_pk_mul_f32 v[8:9], v[8:9], v[154:155]
	v_pk_mul_f32 v[10:11], v[10:11], v[156:157]
	v_pk_mul_f32 v[4:5], v[4:5], v[158:159]
	v_pk_mul_f32 v[6:7], v[6:7], v[162:163]
	v_cvt_pk_bf16_f32 v8, v8, v9
	v_cvt_pk_bf16_f32 v9, v10, v11
	v_cvt_pk_bf16_f32 v10, v4, v5
	v_cvt_pk_bf16_f32 v11, v6, v7
	global_store_dwordx4 v148, v[8:11], s[100:101] offset:256
